# attention loop split into two code paths: waves 4-7 (priority 1) issue all LDS-DMA pieces incl. those of waves 0-3; waves 0-3 issue none and skip the address SALU
# speedup vs baseline: 1.0088x; 1.0067x over previous
; __device__ __forceinline__ float bflo(unsigned u) { return __uint_as_float(u << 16); }
; __device__ __forceinline__ float bfhi(unsigned u) { return __uint_as_float(u & 0xffff0000u); }
; #define DMA_WAIT_BAR() do { asm volatile("s_waitcnt vmcnt(0)" ::: "memory"); __syncthreads(); } while (0)
; #define RD_K(slot) do { const LAS unsigned char* kp_ = L + (slot) * ASLOT; \
;         _Pragma("unroll") for (int st = 0; st < 4; ++st) { kf[2 * st] = *(const LAS bf16x8*)(kp_ + (kb0 ^ (32 * st))); kf[2 * st + 1] = *(const LAS bf16x8*)(kp_ + 8192 + (kb0 ^ (32 * st))); } } while (0)
; __device__ __forceinline__ void attn_unit(LAS unsigned char* L, bf16_t* QKV, size_t rowbase, int S, int h, int qb, float lam, const float* subln, unsigned* kmax) {
;     ...
;         const int seq = rowbase < (size_t)TP ? (int)(rowbase >> 14) : 2 + (int)((rowbase - TP) >> 13);
;         unsigned* kp = kmax + (seq * 16 + 2 * h + hd) * 2;
;         const float kb = sqrtf(__uint_as_float(__hip_atomic_load(kp, __ATOMIC_RELAXED, __HIP_MEMORY_SCOPE_AGENT)) + __uint_as_float(__hip_atomic_load(kp + 1, __ATOMIC_RELAXED, __HIP_MEMORY_SCOPE_AGENT)));
;         float q2 = 0.f;
; #pragma unroll
;         for (int st = 0; st < 4; ++st) { const u32x4 w = __builtin_bit_cast(u32x4, qf[st]);
;             q2 += ((bflo(w.x) * bflo(w.x) + bfhi(w.x) * bfhi(w.x)) + (bflo(w.y) * bflo(w.y) + bfhi(w.y) * bfhi(w.y))) + ((bflo(w.z) * bflo(w.z) + bfhi(w.z) * bfhi(w.z)) + (bflo(w.w) * bflo(w.w) + bfhi(w.w) * bfhi(w.w))); }
;         q2 += __shfl_xor(q2, 32);
;         const float mref = sqrtf(q2) * kb;
; #pragma unroll
;         for (int r = 0; r < 16; ++r) negm[r] = -mref; }
;     DMA_WAIT_BAR();
;     bf16x8 kf[8], va[4], vb[4];
;     ...
;     RD_K(0);
;     __syncthreads();
.LBB0_926:
	s_lshl_b32 s5, s63, 2
	s_lshl_b32 s10, s40, 1
	s_lshl_b32 s4, s22, 5
	s_add_i32 s5, s10, s5
	s_add_i32 s10, s5, s4
	s_lshl_b32 s23, s40, 3
	s_lshl_b64 s[4:5], s[10:11], 2
	s_add_u32 s4, s26, s4
	s_addc_u32 s5, s27, s5
	global_load_dword v25, v157, s[4:5] sc1
	global_load_dword v27, v157, s[4:5] offset:4 sc1
	s_waitcnt vmcnt(5)
	v_and_b32_e32 v3, 0xffff0000, v113
	v_and_b32_e32 v2, 0xffff0000, v112
	v_and_b32_e32 v7, 0xffff0000, v115
	v_and_b32_e32 v6, 0xffff0000, v114
	s_waitcnt vmcnt(4)
	v_and_b32_e32 v11, 0xffff0000, v117
	v_and_b32_e32 v10, 0xffff0000, v116
	v_and_b32_e32 v15, 0xffff0000, v119
	v_and_b32_e32 v14, 0xffff0000, v118
	v_lshlrev_b32_e32 v1, 16, v113
	v_lshlrev_b32_e32 v0, 16, v112
	v_lshlrev_b32_e32 v5, 16, v115
	v_lshlrev_b32_e32 v4, 16, v114
	v_lshlrev_b32_e32 v9, 16, v117
	v_lshlrev_b32_e32 v8, 16, v116
	v_lshlrev_b32_e32 v13, 16, v119
	v_lshlrev_b32_e32 v12, 16, v118
	v_pk_mul_f32 v[2:3], v[2:3], v[2:3]
	v_pk_mul_f32 v[6:7], v[6:7], v[6:7]
	v_pk_mul_f32 v[10:11], v[10:11], v[10:11]
	v_pk_mul_f32 v[14:15], v[14:15], v[14:15]
	s_waitcnt vmcnt(2)
	v_lshlrev_b32_e32 v24, 16, v124
	v_and_b32_e32 v26, 0xffff0000, v124
	v_lshlrev_b32_e32 v28, 16, v125
	v_and_b32_e32 v29, 0xffff0000, v125
	v_pk_fma_f32 v[0:1], v[0:1], v[0:1], v[2:3]
	v_pk_fma_f32 v[2:3], v[4:5], v[4:5], v[6:7]
	v_pk_fma_f32 v[4:5], v[8:9], v[8:9], v[10:11]
	v_pk_fma_f32 v[6:7], v[12:13], v[12:13], v[14:15]
	v_mul_f32_e32 v35, v24, v24
	v_mul_f32_e32 v36, v26, v26
	v_mul_f32_e32 v37, v28, v28
	v_mul_f32_e32 v29, v29, v29
	v_pk_add_f32 v[0:1], v[0:1], v[0:1] op_sel:[0,1] op_sel_hi:[1,0]
	v_pk_add_f32 v[2:3], v[2:3], v[2:3] op_sel:[0,1] op_sel_hi:[1,0]
	v_pk_add_f32 v[4:5], v[4:5], v[4:5] op_sel:[0,1] op_sel_hi:[1,0]
	v_pk_add_f32 v[6:7], v[6:7], v[6:7] op_sel:[0,1] op_sel_hi:[1,0]
	v_mov_b32_e32 v1, v35
	v_mov_b32_e32 v3, v36
	v_mov_b32_e32 v5, v37
	v_mov_b32_e32 v7, v29
	v_pk_add_f32 v[0:1], v[0:1], v[2:3]
	v_pk_add_f32 v[2:3], v[4:5], v[6:7]
	v_and_b32_e32 v17, 0xffff0000, v120
	v_and_b32_e32 v19, 0xffff0000, v121
	v_and_b32_e32 v21, 0xffff0000, v122
	v_and_b32_e32 v23, 0xffff0000, v123
	v_lshlrev_b32_e32 v30, 16, v126
	v_and_b32_e32 v31, 0xffff0000, v126
	v_pk_add_f32 v[0:1], v[0:1], v[2:3]
	v_lshlrev_b32_e32 v16, 16, v120
	v_lshlrev_b32_e32 v18, 16, v121
	v_lshlrev_b32_e32 v20, 16, v122
	v_lshlrev_b32_e32 v22, 16, v123
	v_lshlrev_b32_e32 v32, 16, v127
	v_and_b32_e32 v33, 0xffff0000, v127
	v_mul_f32_e32 v38, v30, v30
	v_mul_f32_e32 v31, v31, v31
	v_mul_f32_e32 v24, v17, v17
	v_mul_f32_e32 v26, v19, v19
	v_mul_f32_e32 v28, v21, v21
	v_mul_f32_e32 v30, v23, v23
	v_mul_f32_e32 v32, v32, v32
	v_mul_f32_e32 v33, v33, v33
	v_pk_fma_f32 v[12:13], v[20:21], v[20:21], v[28:29] op_sel_hi:[1,1,0]
	v_pk_fma_f32 v[14:15], v[22:23], v[22:23], v[30:31] op_sel_hi:[1,1,0]
	v_mov_b32_e32 v13, v32
	v_mov_b32_e32 v15, v33
	v_and_b32_e32 v6, 64, v186
	v_add_u32_e32 v6, 64, v6
	v_bitop3_b32 v34, s23, v171, v181 bitop3:0x36
	v_lshl_add_u32 v34, v34, 4, v172
	v_add_u32_e32 v188, 0, v34
	s_waitcnt vmcnt(0)
	s_barrier
	ds_read_b128 v[80:83], v188
	ds_read_b128 v[128:131], v188 offset:8192
	v_mov_b32_e32 v187, 0
	s_waitcnt vmcnt(1)
	v_pk_fma_f32 v[8:9], v[16:17], v[16:17], v[24:25] op_sel_hi:[1,1,0]
	s_waitcnt vmcnt(0)
	v_add_f32_e32 v2, v27, v25
	v_mul_f32_e32 v3, 0x4f800000, v2
	v_cmp_gt_f32_e32 vcc, s37, v2
	v_pk_fma_f32 v[10:11], v[18:19], v[18:19], v[26:27] op_sel_hi:[1,1,0]
	v_mov_b32_e32 v9, v38
	v_cndmask_b32_e32 v4, v2, v3, vcc
	v_mov_b32_e32 v11, v31
	v_sqrt_f32_e32 v5, v4
	v_pk_add_f32 v[8:9], v[8:9], v[10:11]
	v_pk_add_f32 v[10:11], v[12:13], v[14:15]
	s_add_i32 s24, s42, -1
	v_pk_add_f32 v[2:3], v[8:9], v[10:11]
	s_add_i32 s25, s43, 0x1c000
	v_pk_add_f32 v[0:1], v[0:1], v[2:3]
	v_xor_b32_e32 v3, 32, v186
	v_add_f32_e32 v0, v0, v1
	v_add_u32_e32 v1, -1, v5
	v_fma_f32 v2, -v1, v5, v4
	v_cmp_ge_f32_e64 s[4:5], 0, v2
	v_add_u32_e32 v2, 1, v5
	s_add_i32 s63, s43, 0x1e000
	v_cndmask_b32_e64 v1, v5, v1, s[4:5]
	v_cmp_lt_i32_e64 s[4:5], v3, v6
	v_fma_f32 v5, -v2, v5, v4
	s_mov_b32 s68, 7
	v_cndmask_b32_e64 v3, v186, v3, s[4:5]
	v_lshlrev_b32_e32 v156, 2, v3
	ds_bpermute_b32 v3, v156, v0
	v_cmp_lt_f32_e64 s[4:5], 0, v5
	v_mov_b32_e32 v192, 0
	v_mov_b32_e32 v193, 0
	v_cndmask_b32_e64 v1, v1, v2, s[4:5]
	s_waitcnt lgkmcnt(0)
; __device__ __forceinline__ float bflo(unsigned u) { return __uint_as_float(u << 16); }
; __device__ __forceinline__ float bfhi(unsigned u) { return __uint_as_float(u & 0xffff0000u); }
; #define DMA_WAIT_BAR() do { asm volatile("s_waitcnt vmcnt(0)" ::: "memory"); __syncthreads(); } while (0)
; #define RD_K(slot) do { const LAS unsigned char* kp_ = L + (slot) * ASLOT; \
;         _Pragma("unroll") for (int st = 0; st < 4; ++st) { kf[2 * st] = *(const LAS bf16x8*)(kp_ + (kb0 ^ (32 * st))); kf[2 * st + 1] = *(const LAS bf16x8*)(kp_ + 8192 + (kb0 ^ (32 * st))); } } while (0)
; __device__ __forceinline__ void attn_unit(LAS unsigned char* L, bf16_t* QKV, size_t rowbase, int S, int h, int qb, float lam, const float* subln, unsigned* kmax) {
;     ...
;         const int seq = rowbase < (size_t)TP ? (int)(rowbase >> 14) : 2 + (int)((rowbase - TP) >> 13);
;         unsigned* kp = kmax + (seq * 16 + 2 * h + hd) * 2;
;         const float kb = sqrtf(__uint_as_float(__hip_atomic_load(kp, __ATOMIC_RELAXED, __HIP_MEMORY_SCOPE_AGENT)) + __uint_as_float(__hip_atomic_load(kp + 1, __ATOMIC_RELAXED, __HIP_MEMORY_SCOPE_AGENT)));
;         float q2 = 0.f;
; #pragma unroll
;         for (int st = 0; st < 4; ++st) { const u32x4 w = __builtin_bit_cast(u32x4, qf[st]);
;             q2 += ((bflo(w.x) * bflo(w.x) + bfhi(w.x) * bfhi(w.x)) + (bflo(w.y) * bflo(w.y) + bfhi(w.y) * bfhi(w.y))) + ((bflo(w.z) * bflo(w.z) + bfhi(w.z) * bfhi(w.z)) + (bflo(w.w) * bflo(w.w) + bfhi(w.w) * bfhi(w.w))); }
;         q2 += __shfl_xor(q2, 32);
;         const float mref = sqrtf(q2) * kb;
; #pragma unroll
;         for (int r = 0; r < 16; ++r) negm[r] = -mref; }
;     DMA_WAIT_BAR();
;     bf16x8 kf[8], va[4], vb[4];
;     ...
;     RD_K(0);
;     __syncthreads();
	v_add_f32_e32 v0, v0, v3
	v_mul_f32_e32 v3, 0x4f800000, v0
	v_cmp_gt_f32_e64 s[4:5], s37, v0
	v_mul_f32_e32 v2, 0x37800000, v1
	v_cndmask_b32_e32 v1, v1, v2, vcc
	v_cndmask_b32_e64 v0, v0, v3, s[4:5]
	v_sqrt_f32_e32 v3, v0
	v_cmp_class_f32_e32 vcc, v4, v173
	v_mov_b32_e32 v194, 0
	v_mov_b32_e32 v5, v187
	v_add_u32_e32 v2, -1, v3
	v_cndmask_b32_e32 v1, v1, v4, vcc
	v_fma_f32 v4, -v2, v3, v0
	v_cmp_ge_f32_e32 vcc, 0, v4
	v_add_u32_e32 v4, 1, v3
	v_mov_b32_e32 v6, v187
	v_cndmask_b32_e32 v2, v3, v2, vcc
	v_fma_f32 v3, -v4, v3, v0
	v_cmp_lt_f32_e32 vcc, 0, v3
	v_mov_b32_e32 v7, v187
	v_mov_b32_e32 v8, v187
	v_cndmask_b32_e32 v2, v2, v4, vcc
	v_mul_f32_e32 v3, 0x37800000, v2
	v_cndmask_b32_e64 v2, v2, v3, s[4:5]
	v_cmp_class_f32_e32 vcc, v0, v173
	v_mov_b32_e32 v3, v187
	v_mov_b32_e32 v4, v187
	v_cndmask_b32_e32 v0, v2, v0, vcc
	v_mul_f32_e64 v64, v0, -v1
	v_xor_b32_e32 v0, 32, v34
	v_add_u32_e32 v189, 0, v0
	v_xor_b32_e32 v0, 64, v34
	v_add_u32_e32 v190, 0, v0
	v_xor_b32_e32 v0, 0x60, v34
	v_add_u32_e32 v191, 0, v0
	ds_read_b128 v[132:135], v189
	ds_read_b128 v[136:139], v189 offset:8192
	ds_read_b128 v[140:143], v190
	ds_read_b128 v[144:147], v190 offset:8192
	ds_read_b128 v[148:151], v191
	ds_read_b128 v[152:155], v191 offset:8192
	v_mov_b32_e32 v65, v64
	v_mov_b32_e32 v66, v64
	v_mov_b32_e32 v67, v64
	v_mov_b32_e32 v68, v64
	v_mov_b32_e32 v69, v64
	v_mov_b32_e32 v70, v64
	v_mov_b32_e32 v71, v64
	v_mov_b32_e32 v72, v64
	v_mov_b32_e32 v73, v64
	v_mov_b32_e32 v74, v64
	v_mov_b32_e32 v75, v64
	v_mov_b32_e32 v76, v64
	v_mov_b32_e32 v77, v64
	v_mov_b32_e32 v78, v64
	v_mov_b32_e32 v79, v64
	v_mov_b32_e32 v0, 0
	v_mov_b32_e32 v1, v187
	v_mov_b32_e32 v2, v187
	v_mov_b32_e32 v9, v187
	v_mov_b32_e32 v10, v187
	v_mov_b32_e32 v11, v187
	v_mov_b32_e32 v12, v187
	v_mov_b32_e32 v13, v187
	v_mov_b32_e32 v14, v187
	v_mov_b32_e32 v15, v187
	v_mov_b32_e32 v16, 0
	v_mov_b32_e32 v17, v187
	v_mov_b32_e32 v18, v187
	v_mov_b32_e32 v19, v187
	v_mov_b32_e32 v20, v187
	v_mov_b32_e32 v21, v187
	v_mov_b32_e32 v22, v187
	v_mov_b32_e32 v23, v187
	v_mov_b32_e32 v24, v187
	v_mov_b32_e32 v25, v187
	v_mov_b32_e32 v26, v187
	v_mov_b32_e32 v27, v187
	v_mov_b32_e32 v28, v187
	v_mov_b32_e32 v29, v187
	v_mov_b32_e32 v30, v187
	v_mov_b32_e32 v31, v187
	v_mov_b32_e32 v32, 0
	v_mov_b32_e32 v33, v187
	v_mov_b32_e32 v34, v187
	v_mov_b32_e32 v35, v187
	v_mov_b32_e32 v36, v187
	v_mov_b32_e32 v37, v187
	v_mov_b32_e32 v38, v187
	v_mov_b32_e32 v39, v187
	v_mov_b32_e32 v40, v187
	v_mov_b32_e32 v41, v187
	v_mov_b32_e32 v42, v187
	v_mov_b32_e32 v43, v187
	v_mov_b32_e32 v44, v187
	v_mov_b32_e32 v45, v187
	v_mov_b32_e32 v46, v187
	v_mov_b32_e32 v47, v187
	v_mov_b32_e32 v48, 0
	v_mov_b32_e32 v49, v187
	v_mov_b32_e32 v50, v187
	v_mov_b32_e32 v51, v187
	v_mov_b32_e32 v52, v187
	v_mov_b32_e32 v53, v187
	v_mov_b32_e32 v54, v187
	v_mov_b32_e32 v55, v187
	v_mov_b32_e32 v56, v187
	v_mov_b32_e32 v57, v187
	v_mov_b32_e32 v58, v187
	v_mov_b32_e32 v59, v187
	v_mov_b32_e32 v60, v187
	v_mov_b32_e32 v61, v187
	v_mov_b32_e32 v62, v187
	v_mov_b32_e32 v63, v187
	s_add_u32 s22, s20, 0x10000
	s_addc_u32 s23, s21, 0
	s_add_u32 s4, s20, 0x18000
	s_addc_u32 s5, s21, 0
	ds_read_b64_tr_b16 v[224:225], v174
	ds_read_b64_tr_b16 v[226:227], v175 offset:2048
	ds_read_b64_tr_b16 v[228:229], v176
	ds_read_b64_tr_b16 v[230:231], v177 offset:2048
	ds_read_b64_tr_b16 v[232:233], v178
	ds_read_b64_tr_b16 v[234:235], v179 offset:2048
	ds_read_b64_tr_b16 v[236:237], v183
	ds_read_b64_tr_b16 v[238:239], v184 offset:2048
	v_add_u32_e32 v254, 0x4000, v163
	v_add_u32_e32 v255, 0x100, v163
	v_add_u32_e32 v253, 0x4100, v163
	v_add_u32_e32 v250, 0xffffe000, v163
	v_add_u32_e32 v251, 0x2000, v163
	v_add_u32_e32 v252, 0xffffe100, v163
	v_add_u32_e32 v195, 0x2100, v163
	s_waitcnt lgkmcnt(0)
	s_barrier
	s_cmp_eq_u32 s40, 1
	s_cbranch_scc0 .LBB0_927
	s_setprio 1
	s_branch .Lattn_G
.LBB0_927:
	s_add_i32 s69, s68, -3
	v_mfma_f32_32x32x16_bf16 v[96:111], v[132:135], v[116:119], v[64:79]
	v_mfma_f32_32x32x16_bf16 v[96:111], v[140:143], v[120:123], v[96:111]
	s_waitcnt lgkmcnt(10)
	v_mfma_f32_32x32x16_bf16 v[96:111], v[148:151], v[124:127], v[96:111]
	ds_read_b64_tr_b16 v[132:133], v176 offset:4096
	ds_read_b64_tr_b16 v[134:135], v177 offset:6144
	s_waitcnt lgkmcnt(10)
	v_mfma_f32_32x32x16_bf16 v[96:111], v[80:83], v[112:115], v[96:111]
	ds_read_b64_tr_b16 v[140:141], v183 offset:4096
	ds_read_b64_tr_b16 v[142:143], v184 offset:6144
	v_mfma_f32_32x32x16_bf16 v[80:95], v[128:131], v[112:115], v[64:79]
	ds_read_b64_tr_b16 v[128:129], v174 offset:4096
	ds_read_b64_tr_b16 v[130:131], v175 offset:6144
	v_mfma_f32_32x32x16_bf16 v[80:95], v[136:139], v[116:119], v[80:95]
	s_nop 4
	v_mfma_f32_32x32x16_bf16 v[80:95], v[144:147], v[120:123], v[80:95]
	v_exp_f32_e32 v96, v96
	v_exp_f32_e32 v97, v97
	v_exp_f32_e32 v98, v98
	v_mfma_f32_32x32x16_bf16 v[80:95], v[152:155], v[124:127], v[80:95]
	v_exp_f32_e32 v99, v99
	v_exp_f32_e32 v100, v100
	v_exp_f32_e32 v101, v101
	v_exp_f32_e32 v102, v102
	v_exp_f32_e32 v103, v103
	v_cvt_pk_bf16_f32 v208, v96, v97
	v_cvt_pk_bf16_f32 v209, v98, v99
	v_cvt_pk_bf16_f32 v210, v100, v101
	v_cvt_pk_bf16_f32 v211, v102, v103
	v_exp_f32_e32 v104, v104
	v_exp_f32_e32 v105, v105
	s_waitcnt lgkmcnt(6)
	v_mfma_f32_32x32x16_bf16 v[48:63], v[224:227], v[208:211], v[48:63]
	v_exp_f32_e32 v106, v106
	v_exp_f32_e32 v107, v107
	v_exp_f32_e32 v108, v108
	ds_read_b64_tr_b16 v[136:137], v178 offset:4096
	ds_read_b64_tr_b16 v[138:139], v179 offset:6144
	v_mfma_f32_32x32x16_bf16 v[32:47], v[228:231], v[208:211], v[32:47]
	v_exp_f32_e32 v109, v109
	v_exp_f32_e32 v110, v110
	v_exp_f32_e32 v111, v111
	ds_read_b64_tr_b16 v[144:145], v174 offset:8192
	ds_read_b64_tr_b16 v[146:147], v175 offset:10240
	v_mfma_f32_32x32x16_bf16 v[16:31], v[232:235], v[208:211], v[16:31]
	v_cvt_pk_bf16_f32 v212, v104, v105
	v_cvt_pk_bf16_f32 v213, v106, v107
	v_cvt_pk_bf16_f32 v214, v108, v109
	v_cvt_pk_bf16_f32 v215, v110, v111
	v_add_f32_e32 v187, v96, v187
	v_add_f32_e32 v192, v97, v192
	ds_read_b64_tr_b16 v[148:149], v176 offset:8192
	ds_read_b64_tr_b16 v[150:151], v177 offset:10240
	v_mfma_f32_32x32x16_bf16 v[0:15], v[236:239], v[208:211], v[0:15]
	v_add_f32_e32 v193, v98, v193
	v_add_f32_e32 v194, v99, v194
	v_add_f32_e32 v187, v100, v187
	v_add_f32_e32 v192, v101, v192
	v_add_f32_e32 v193, v102, v193
	v_add_f32_e32 v194, v103, v194
	ds_read_b64_tr_b16 v[152:153], v178 offset:8192
	ds_read_b64_tr_b16 v[154:155], v179 offset:10240
	s_waitcnt lgkmcnt(6)
	v_mfma_f32_32x32x16_bf16 v[48:63], v[128:131], v[212:215], v[48:63]
	v_exp_f32_e32 v80, v80
	v_exp_f32_e32 v81, v81
	v_exp_f32_e32 v82, v82
	ds_read_b64_tr_b16 v[240:241], v183 offset:8192
	ds_read_b64_tr_b16 v[242:243], v184 offset:10240
	ds_read_b128 v[128:131], v188 offset:24576
	v_mfma_f32_32x32x16_bf16 v[32:47], v[132:135], v[212:215], v[32:47]
	v_exp_f32_e32 v83, v83
	v_exp_f32_e32 v84, v84
	v_exp_f32_e32 v85, v85
	ds_read_b64_tr_b16 v[196:197], v174 offset:12288
	ds_read_b64_tr_b16 v[198:199], v175 offset:14336
	ds_read_b128 v[132:135], v189 offset:16384
	v_mfma_f32_32x32x16_bf16 v[16:31], v[136:139], v[212:215], v[16:31]
	v_exp_f32_e32 v86, v86
	v_exp_f32_e32 v87, v87
	v_cvt_pk_bf16_f32 v216, v80, v81
	v_cvt_pk_bf16_f32 v217, v82, v83
	ds_read_b64_tr_b16 v[200:201], v176 offset:12288
	ds_read_b64_tr_b16 v[202:203], v177 offset:14336
	ds_read_b128 v[136:139], v189 offset:24576
	v_mfma_f32_32x32x16_bf16 v[0:15], v[140:143], v[212:215], v[0:15]
	v_cvt_pk_bf16_f32 v218, v84, v85
	v_cvt_pk_bf16_f32 v219, v86, v87
	v_add_f32_e32 v187, v104, v187
	v_add_f32_e32 v192, v105, v192
	v_add_f32_e32 v193, v106, v193
	v_add_f32_e32 v194, v107, v194
	s_waitcnt lgkmcnt(12)
	ds_read_b64_tr_b16 v[204:205], v178 offset:12288
	ds_read_b64_tr_b16 v[206:207], v179 offset:14336
	ds_read_b128 v[140:143], v190 offset:16384
	s_waitcnt lgkmcnt(10)
	v_mfma_f32_32x32x16_bf16 v[48:63], v[144:147], v[216:219], v[48:63]
	v_exp_f32_e32 v88, v88
	v_exp_f32_e32 v89, v89
	v_exp_f32_e32 v90, v90
	ds_read_b64_tr_b16 v[246:247], v183 offset:12288
	ds_read_b64_tr_b16 v[248:249], v184 offset:14336
	ds_read_b128 v[144:147], v190 offset:24576
	v_mfma_f32_32x32x16_bf16 v[32:47], v[148:151], v[216:219], v[32:47]
	v_exp_f32_e32 v91, v91
	v_exp_f32_e32 v92, v92
	v_exp_f32_e32 v93, v93
	ds_read_b128 v[148:151], v191 offset:16384
	v_mfma_f32_32x32x16_bf16 v[16:31], v[152:155], v[216:219], v[16:31]
	v_exp_f32_e32 v94, v94
	v_exp_f32_e32 v95, v95
	v_cvt_pk_bf16_f32 v220, v88, v89
	v_cvt_pk_bf16_f32 v221, v90, v91
	ds_read_b128 v[152:155], v191 offset:24576
	v_mfma_f32_32x32x16_bf16 v[0:15], v[240:243], v[216:219], v[0:15]
	v_cvt_pk_bf16_f32 v222, v92, v93
	v_cvt_pk_bf16_f32 v223, v94, v95
	v_add_f32_e32 v187, v80, v187
	v_add_f32_e32 v192, v81, v192
	v_add_f32_e32 v193, v82, v193
	v_add_f32_e32 v194, v83, v194
	s_waitcnt lgkmcnt(3)
	v_mfma_f32_32x32x16_bf16 v[48:63], v[196:199], v[220:223], v[48:63]
	v_add_f32_e32 v187, v108, v187
	v_add_f32_e32 v192, v109, v192
	v_add_f32_e32 v193, v110, v193
	v_add_f32_e32 v194, v111, v194
	v_add_f32_e32 v187, v84, v187
	v_add_f32_e32 v192, v85, v192
	ds_read_b128 v[80:83], v188 offset:16384
	ds_read_b64_tr_b16 v[224:225], v174 offset:16384
	ds_read_b64_tr_b16 v[226:227], v175 offset:18432
	v_mfma_f32_32x32x16_bf16 v[32:47], v[200:203], v[220:223], v[32:47]
	v_add_f32_e32 v193, v86, v193
	v_add_f32_e32 v194, v87, v194
	v_add_f32_e32 v187, v88, v187
	v_add_f32_e32 v192, v89, v192
	v_add_f32_e32 v193, v90, v193
	v_add_f32_e32 v194, v91, v194
	ds_read_b64_tr_b16 v[228:229], v176 offset:16384
	ds_read_b64_tr_b16 v[230:231], v177 offset:18432
	v_mfma_f32_32x32x16_bf16 v[16:31], v[204:207], v[220:223], v[16:31]
	v_add_f32_e32 v187, v92, v187
	v_add_f32_e32 v192, v93, v192
	v_add_f32_e32 v193, v94, v193
	v_add_f32_e32 v194, v95, v194
	ds_read_b64_tr_b16 v[232:233], v178 offset:16384
	ds_read_b64_tr_b16 v[234:235], v179 offset:18432
	v_mfma_f32_32x32x16_bf16 v[0:15], v[246:249], v[220:223], v[0:15]
	ds_read_b64_tr_b16 v[236:237], v183 offset:16384
	ds_read_b64_tr_b16 v[238:239], v184 offset:18432
	s_barrier
	v_mfma_f32_32x32x16_bf16 v[96:111], v[132:135], v[116:119], v[64:79]
	v_mfma_f32_32x32x16_bf16 v[96:111], v[140:143], v[120:123], v[96:111]
	s_waitcnt lgkmcnt(10)
	v_mfma_f32_32x32x16_bf16 v[96:111], v[148:151], v[124:127], v[96:111]
	ds_read_b64_tr_b16 v[132:133], v176 offset:20480
	ds_read_b64_tr_b16 v[134:135], v177 offset:22528
	s_waitcnt lgkmcnt(10)
	v_mfma_f32_32x32x16_bf16 v[96:111], v[80:83], v[112:115], v[96:111]
	ds_read_b64_tr_b16 v[140:141], v183 offset:20480
	ds_read_b64_tr_b16 v[142:143], v184 offset:22528
	v_mfma_f32_32x32x16_bf16 v[80:95], v[128:131], v[112:115], v[64:79]
	ds_read_b64_tr_b16 v[128:129], v174 offset:20480
	ds_read_b64_tr_b16 v[130:131], v175 offset:22528
	v_mfma_f32_32x32x16_bf16 v[80:95], v[136:139], v[116:119], v[80:95]
	s_nop 4
	v_mfma_f32_32x32x16_bf16 v[80:95], v[144:147], v[120:123], v[80:95]
	v_exp_f32_e32 v96, v96
	v_exp_f32_e32 v97, v97
	v_exp_f32_e32 v98, v98
	v_mfma_f32_32x32x16_bf16 v[80:95], v[152:155], v[124:127], v[80:95]
	v_exp_f32_e32 v99, v99
	v_exp_f32_e32 v100, v100
	v_exp_f32_e32 v101, v101
	v_exp_f32_e32 v102, v102
	v_exp_f32_e32 v103, v103
	v_cvt_pk_bf16_f32 v208, v96, v97
	v_cvt_pk_bf16_f32 v209, v98, v99
	v_cvt_pk_bf16_f32 v210, v100, v101
	v_cvt_pk_bf16_f32 v211, v102, v103
	v_exp_f32_e32 v104, v104
	v_exp_f32_e32 v105, v105
	s_waitcnt lgkmcnt(6)
	v_mfma_f32_32x32x16_bf16 v[48:63], v[224:227], v[208:211], v[48:63]
	v_exp_f32_e32 v106, v106
	v_exp_f32_e32 v107, v107
	v_exp_f32_e32 v108, v108
	ds_read_b64_tr_b16 v[136:137], v178 offset:20480
	ds_read_b64_tr_b16 v[138:139], v179 offset:22528
	v_mfma_f32_32x32x16_bf16 v[32:47], v[228:231], v[208:211], v[32:47]
	v_exp_f32_e32 v109, v109
	v_exp_f32_e32 v110, v110
	v_exp_f32_e32 v111, v111
	ds_read_b64_tr_b16 v[144:145], v174 offset:24576
	ds_read_b64_tr_b16 v[146:147], v175 offset:26624
	v_mfma_f32_32x32x16_bf16 v[16:31], v[232:235], v[208:211], v[16:31]
	v_cvt_pk_bf16_f32 v212, v104, v105
	v_cvt_pk_bf16_f32 v213, v106, v107
	v_cvt_pk_bf16_f32 v214, v108, v109
	v_cvt_pk_bf16_f32 v215, v110, v111
	v_add_f32_e32 v187, v96, v187
	v_add_f32_e32 v192, v97, v192
	ds_read_b64_tr_b16 v[148:149], v176 offset:24576
	ds_read_b64_tr_b16 v[150:151], v177 offset:26624
	v_mfma_f32_32x32x16_bf16 v[0:15], v[236:239], v[208:211], v[0:15]
	v_add_f32_e32 v193, v98, v193
	v_add_f32_e32 v194, v99, v194
	v_add_f32_e32 v187, v100, v187
	v_add_f32_e32 v192, v101, v192
	v_add_f32_e32 v193, v102, v193
	v_add_f32_e32 v194, v103, v194
	ds_read_b64_tr_b16 v[152:153], v178 offset:24576
	ds_read_b64_tr_b16 v[154:155], v179 offset:26624
	s_waitcnt lgkmcnt(6)
	v_mfma_f32_32x32x16_bf16 v[48:63], v[128:131], v[212:215], v[48:63]
	v_exp_f32_e32 v80, v80
	v_exp_f32_e32 v81, v81
	v_exp_f32_e32 v82, v82
	ds_read_b64_tr_b16 v[240:241], v183 offset:24576
	ds_read_b64_tr_b16 v[242:243], v184 offset:26624
	ds_read_b128 v[128:131], v188 offset:40960
	v_mfma_f32_32x32x16_bf16 v[32:47], v[132:135], v[212:215], v[32:47]
	v_exp_f32_e32 v83, v83
	v_exp_f32_e32 v84, v84
	v_exp_f32_e32 v85, v85
	ds_read_b64_tr_b16 v[196:197], v174 offset:28672
	ds_read_b64_tr_b16 v[198:199], v175 offset:30720
	ds_read_b128 v[132:135], v189 offset:32768
	v_mfma_f32_32x32x16_bf16 v[16:31], v[136:139], v[212:215], v[16:31]
	v_exp_f32_e32 v86, v86
	v_exp_f32_e32 v87, v87
	v_cvt_pk_bf16_f32 v216, v80, v81
	v_cvt_pk_bf16_f32 v217, v82, v83
	ds_read_b64_tr_b16 v[200:201], v176 offset:28672
	ds_read_b64_tr_b16 v[202:203], v177 offset:30720
	ds_read_b128 v[136:139], v189 offset:40960
	v_mfma_f32_32x32x16_bf16 v[0:15], v[140:143], v[212:215], v[0:15]
	v_cvt_pk_bf16_f32 v218, v84, v85
	v_cvt_pk_bf16_f32 v219, v86, v87
	v_add_f32_e32 v187, v104, v187
	v_add_f32_e32 v192, v105, v192
	v_add_f32_e32 v193, v106, v193
	v_add_f32_e32 v194, v107, v194
	s_waitcnt lgkmcnt(12)
	ds_read_b64_tr_b16 v[204:205], v178 offset:28672
	ds_read_b64_tr_b16 v[206:207], v179 offset:30720
	ds_read_b128 v[140:143], v190 offset:32768
	s_waitcnt lgkmcnt(10)
	v_mfma_f32_32x32x16_bf16 v[48:63], v[144:147], v[216:219], v[48:63]
	v_exp_f32_e32 v88, v88
	v_exp_f32_e32 v89, v89
	v_exp_f32_e32 v90, v90
	ds_read_b64_tr_b16 v[246:247], v183 offset:28672
	ds_read_b64_tr_b16 v[248:249], v184 offset:30720
	ds_read_b128 v[144:147], v190 offset:40960
	v_mfma_f32_32x32x16_bf16 v[32:47], v[148:151], v[216:219], v[32:47]
	v_exp_f32_e32 v91, v91
	v_exp_f32_e32 v92, v92
	v_exp_f32_e32 v93, v93
	ds_read_b128 v[148:151], v191 offset:32768
	v_mfma_f32_32x32x16_bf16 v[16:31], v[152:155], v[216:219], v[16:31]
	v_exp_f32_e32 v94, v94
	v_exp_f32_e32 v95, v95
	v_cvt_pk_bf16_f32 v220, v88, v89
	v_cvt_pk_bf16_f32 v221, v90, v91
	ds_read_b128 v[152:155], v191 offset:40960
	v_mfma_f32_32x32x16_bf16 v[0:15], v[240:243], v[216:219], v[0:15]
	v_cvt_pk_bf16_f32 v222, v92, v93
	v_cvt_pk_bf16_f32 v223, v94, v95
	v_add_f32_e32 v187, v80, v187
	v_add_f32_e32 v192, v81, v192
	v_add_f32_e32 v193, v82, v193
	v_add_f32_e32 v194, v83, v194
	s_waitcnt lgkmcnt(3)
	v_mfma_f32_32x32x16_bf16 v[48:63], v[196:199], v[220:223], v[48:63]
	v_add_f32_e32 v187, v108, v187
	v_add_f32_e32 v192, v109, v192
	v_add_f32_e32 v193, v110, v193
	v_add_f32_e32 v194, v111, v194
	v_add_f32_e32 v187, v84, v187
	v_add_f32_e32 v192, v85, v192
	ds_read_b128 v[80:83], v188 offset:32768
	ds_read_b64_tr_b16 v[224:225], v174 offset:32768
	ds_read_b64_tr_b16 v[226:227], v175 offset:34816
	v_mfma_f32_32x32x16_bf16 v[32:47], v[200:203], v[220:223], v[32:47]
	v_add_f32_e32 v193, v86, v193
	v_add_f32_e32 v194, v87, v194
	v_add_f32_e32 v187, v88, v187
	v_add_f32_e32 v192, v89, v192
	v_add_f32_e32 v193, v90, v193
	v_add_f32_e32 v194, v91, v194
	ds_read_b64_tr_b16 v[228:229], v176 offset:32768
	ds_read_b64_tr_b16 v[230:231], v177 offset:34816
	v_mfma_f32_32x32x16_bf16 v[16:31], v[204:207], v[220:223], v[16:31]
	v_add_f32_e32 v187, v92, v187
	v_add_f32_e32 v192, v93, v192
	v_add_f32_e32 v193, v94, v193
	v_add_f32_e32 v194, v95, v194
	ds_read_b64_tr_b16 v[232:233], v178 offset:32768
	ds_read_b64_tr_b16 v[234:235], v179 offset:34816
	v_mfma_f32_32x32x16_bf16 v[0:15], v[246:249], v[220:223], v[0:15]
	ds_read_b64_tr_b16 v[236:237], v183 offset:32768
	ds_read_b64_tr_b16 v[238:239], v184 offset:34816
	s_barrier
	v_mfma_f32_32x32x16_bf16 v[96:111], v[132:135], v[116:119], v[64:79]
	v_mfma_f32_32x32x16_bf16 v[96:111], v[140:143], v[120:123], v[96:111]
	s_waitcnt lgkmcnt(10)
	v_mfma_f32_32x32x16_bf16 v[96:111], v[148:151], v[124:127], v[96:111]
	ds_read_b64_tr_b16 v[132:133], v176 offset:36864
	ds_read_b64_tr_b16 v[134:135], v177 offset:38912
	s_waitcnt lgkmcnt(10)
	v_mfma_f32_32x32x16_bf16 v[96:111], v[80:83], v[112:115], v[96:111]
	ds_read_b64_tr_b16 v[140:141], v183 offset:36864
	ds_read_b64_tr_b16 v[142:143], v184 offset:38912
	v_mfma_f32_32x32x16_bf16 v[80:95], v[128:131], v[112:115], v[64:79]
	ds_read_b64_tr_b16 v[128:129], v174 offset:36864
	ds_read_b64_tr_b16 v[130:131], v175 offset:38912
	v_mfma_f32_32x32x16_bf16 v[80:95], v[136:139], v[116:119], v[80:95]
	s_nop 4
	v_mfma_f32_32x32x16_bf16 v[80:95], v[144:147], v[120:123], v[80:95]
	v_exp_f32_e32 v96, v96
	v_exp_f32_e32 v97, v97
	v_exp_f32_e32 v98, v98
	v_mfma_f32_32x32x16_bf16 v[80:95], v[152:155], v[124:127], v[80:95]
	v_exp_f32_e32 v99, v99
	v_exp_f32_e32 v100, v100
	v_exp_f32_e32 v101, v101
	v_exp_f32_e32 v102, v102
	v_exp_f32_e32 v103, v103
	v_cvt_pk_bf16_f32 v208, v96, v97
	v_cvt_pk_bf16_f32 v209, v98, v99
	v_cvt_pk_bf16_f32 v210, v100, v101
	v_cvt_pk_bf16_f32 v211, v102, v103
	v_exp_f32_e32 v104, v104
	v_exp_f32_e32 v105, v105
	s_waitcnt lgkmcnt(6)
	v_mfma_f32_32x32x16_bf16 v[48:63], v[224:227], v[208:211], v[48:63]
	v_exp_f32_e32 v106, v106
	v_exp_f32_e32 v107, v107
	v_exp_f32_e32 v108, v108
	ds_read_b64_tr_b16 v[136:137], v178 offset:36864
	ds_read_b64_tr_b16 v[138:139], v179 offset:38912
	v_mfma_f32_32x32x16_bf16 v[32:47], v[228:231], v[208:211], v[32:47]
	v_exp_f32_e32 v109, v109
	v_exp_f32_e32 v110, v110
	v_exp_f32_e32 v111, v111
	ds_read_b64_tr_b16 v[144:145], v174 offset:40960
	ds_read_b64_tr_b16 v[146:147], v175 offset:43008
	v_mfma_f32_32x32x16_bf16 v[16:31], v[232:235], v[208:211], v[16:31]
	v_cvt_pk_bf16_f32 v212, v104, v105
	v_cvt_pk_bf16_f32 v213, v106, v107
	v_cvt_pk_bf16_f32 v214, v108, v109
	v_cvt_pk_bf16_f32 v215, v110, v111
	v_add_f32_e32 v187, v96, v187
	v_add_f32_e32 v192, v97, v192
	ds_read_b64_tr_b16 v[148:149], v176 offset:40960
	ds_read_b64_tr_b16 v[150:151], v177 offset:43008
	v_mfma_f32_32x32x16_bf16 v[0:15], v[236:239], v[208:211], v[0:15]
	v_add_f32_e32 v193, v98, v193
	v_add_f32_e32 v194, v99, v194
	v_add_f32_e32 v187, v100, v187
	v_add_f32_e32 v192, v101, v192
	v_add_f32_e32 v193, v102, v193
	v_add_f32_e32 v194, v103, v194
	ds_read_b64_tr_b16 v[152:153], v178 offset:40960
	ds_read_b64_tr_b16 v[154:155], v179 offset:43008
	s_waitcnt lgkmcnt(6)
	v_mfma_f32_32x32x16_bf16 v[48:63], v[128:131], v[212:215], v[48:63]
	v_exp_f32_e32 v80, v80
	v_exp_f32_e32 v81, v81
	v_exp_f32_e32 v82, v82
	ds_read_b64_tr_b16 v[240:241], v183 offset:40960
	ds_read_b64_tr_b16 v[242:243], v184 offset:43008
	ds_read_b128 v[128:131], v188 offset:57344
	v_mfma_f32_32x32x16_bf16 v[32:47], v[132:135], v[212:215], v[32:47]
	v_exp_f32_e32 v83, v83
	v_exp_f32_e32 v84, v84
	v_exp_f32_e32 v85, v85
	ds_read_b64_tr_b16 v[196:197], v174 offset:45056
	ds_read_b64_tr_b16 v[198:199], v175 offset:47104
	ds_read_b128 v[132:135], v189 offset:49152
	v_mfma_f32_32x32x16_bf16 v[16:31], v[136:139], v[212:215], v[16:31]
	v_exp_f32_e32 v86, v86
	v_exp_f32_e32 v87, v87
	v_cvt_pk_bf16_f32 v216, v80, v81
	v_cvt_pk_bf16_f32 v217, v82, v83
	ds_read_b64_tr_b16 v[200:201], v176 offset:45056
	ds_read_b64_tr_b16 v[202:203], v177 offset:47104
	ds_read_b128 v[136:139], v189 offset:57344
	v_mfma_f32_32x32x16_bf16 v[0:15], v[140:143], v[212:215], v[0:15]
	v_cvt_pk_bf16_f32 v218, v84, v85
	v_cvt_pk_bf16_f32 v219, v86, v87
	v_add_f32_e32 v187, v104, v187
	v_add_f32_e32 v192, v105, v192
	v_add_f32_e32 v193, v106, v193
	v_add_f32_e32 v194, v107, v194
	s_waitcnt lgkmcnt(12)
	ds_read_b64_tr_b16 v[204:205], v178 offset:45056
	ds_read_b64_tr_b16 v[206:207], v179 offset:47104
	ds_read_b128 v[140:143], v190 offset:49152
	s_waitcnt lgkmcnt(10)
	v_mfma_f32_32x32x16_bf16 v[48:63], v[144:147], v[216:219], v[48:63]
	v_exp_f32_e32 v88, v88
	v_exp_f32_e32 v89, v89
	v_exp_f32_e32 v90, v90
	ds_read_b64_tr_b16 v[246:247], v183 offset:45056
	ds_read_b64_tr_b16 v[248:249], v184 offset:47104
	ds_read_b128 v[144:147], v190 offset:57344
	v_mfma_f32_32x32x16_bf16 v[32:47], v[148:151], v[216:219], v[32:47]
	v_exp_f32_e32 v91, v91
	v_exp_f32_e32 v92, v92
	v_exp_f32_e32 v93, v93
	ds_read_b128 v[148:151], v191 offset:49152
	v_mfma_f32_32x32x16_bf16 v[16:31], v[152:155], v[216:219], v[16:31]
	v_exp_f32_e32 v94, v94
	v_exp_f32_e32 v95, v95
	v_cvt_pk_bf16_f32 v220, v88, v89
	v_cvt_pk_bf16_f32 v221, v90, v91
	ds_read_b128 v[152:155], v191 offset:57344
	v_mfma_f32_32x32x16_bf16 v[0:15], v[240:243], v[216:219], v[0:15]
	v_cvt_pk_bf16_f32 v222, v92, v93
	v_cvt_pk_bf16_f32 v223, v94, v95
	v_add_f32_e32 v187, v80, v187
	v_add_f32_e32 v192, v81, v192
	v_add_f32_e32 v193, v82, v193
	v_add_f32_e32 v194, v83, v194
	s_waitcnt lgkmcnt(3)
	v_mfma_f32_32x32x16_bf16 v[48:63], v[196:199], v[220:223], v[48:63]
	v_add_f32_e32 v187, v108, v187
	v_add_f32_e32 v192, v109, v192
	v_add_f32_e32 v193, v110, v193
	v_add_f32_e32 v194, v111, v194
	v_add_f32_e32 v187, v84, v187
	v_add_f32_e32 v192, v85, v192
	ds_read_b128 v[80:83], v188 offset:49152
	ds_read_b64_tr_b16 v[224:225], v174 offset:49152
	ds_read_b64_tr_b16 v[226:227], v175 offset:51200
	v_mfma_f32_32x32x16_bf16 v[32:47], v[200:203], v[220:223], v[32:47]
	v_add_f32_e32 v193, v86, v193
	v_add_f32_e32 v194, v87, v194
	v_add_f32_e32 v187, v88, v187
	v_add_f32_e32 v192, v89, v192
	v_add_f32_e32 v193, v90, v193
	v_add_f32_e32 v194, v91, v194
	ds_read_b64_tr_b16 v[228:229], v176 offset:49152
	ds_read_b64_tr_b16 v[230:231], v177 offset:51200
	v_mfma_f32_32x32x16_bf16 v[16:31], v[204:207], v[220:223], v[16:31]
	v_add_f32_e32 v187, v92, v187
	v_add_f32_e32 v192, v93, v192
	v_add_f32_e32 v193, v94, v193
	v_add_f32_e32 v194, v95, v194
	ds_read_b64_tr_b16 v[232:233], v178 offset:49152
	ds_read_b64_tr_b16 v[234:235], v179 offset:51200
	v_mfma_f32_32x32x16_bf16 v[0:15], v[246:249], v[220:223], v[0:15]
	ds_read_b64_tr_b16 v[236:237], v183 offset:49152
	ds_read_b64_tr_b16 v[238:239], v184 offset:51200
	s_barrier
; __device__ __forceinline__ void attn_unit(LAS unsigned char* L, bf16_t* QKV, size_t rowbase, int S, int h, int qb, float lam, const float* subln, unsigned* kmax) {
;     ...
;     for (int t = 0; t < NT; t += 4) { TILE(t, 0); TILE(t + 1, 1); TILE(t + 2, 2); TILE(t + 3, 3); }
	v_mfma_f32_32x32x16_bf16 v[96:111], v[132:135], v[116:119], v[64:79]
	v_mfma_f32_32x32x16_bf16 v[96:111], v[140:143], v[120:123], v[96:111]
	s_waitcnt lgkmcnt(10)
	v_mfma_f32_32x32x16_bf16 v[96:111], v[148:151], v[124:127], v[96:111]
	ds_read_b64_tr_b16 v[132:133], v176 offset:53248
	ds_read_b64_tr_b16 v[134:135], v177 offset:55296
	s_waitcnt lgkmcnt(10)
	v_mfma_f32_32x32x16_bf16 v[96:111], v[80:83], v[112:115], v[96:111]
	ds_read_b64_tr_b16 v[140:141], v183 offset:53248
	ds_read_b64_tr_b16 v[142:143], v184 offset:55296
	v_mfma_f32_32x32x16_bf16 v[80:95], v[128:131], v[112:115], v[64:79]
	ds_read_b64_tr_b16 v[128:129], v174 offset:53248
	ds_read_b64_tr_b16 v[130:131], v175 offset:55296
	v_mfma_f32_32x32x16_bf16 v[80:95], v[136:139], v[116:119], v[80:95]
	s_nop 4
	v_mfma_f32_32x32x16_bf16 v[80:95], v[144:147], v[120:123], v[80:95]
	v_exp_f32_e32 v96, v96
	v_exp_f32_e32 v97, v97
	v_exp_f32_e32 v98, v98
	v_mfma_f32_32x32x16_bf16 v[80:95], v[152:155], v[124:127], v[80:95]
	v_exp_f32_e32 v99, v99
	v_exp_f32_e32 v100, v100
	v_exp_f32_e32 v101, v101
	v_exp_f32_e32 v102, v102
	v_exp_f32_e32 v103, v103
	v_cvt_pk_bf16_f32 v208, v96, v97
	v_cvt_pk_bf16_f32 v209, v98, v99
	v_cvt_pk_bf16_f32 v210, v100, v101
	v_cvt_pk_bf16_f32 v211, v102, v103
	v_exp_f32_e32 v104, v104
	v_exp_f32_e32 v105, v105
	s_waitcnt lgkmcnt(6)
	v_mfma_f32_32x32x16_bf16 v[48:63], v[224:227], v[208:211], v[48:63]
	v_exp_f32_e32 v106, v106
	v_exp_f32_e32 v107, v107
	v_exp_f32_e32 v108, v108
	ds_read_b64_tr_b16 v[136:137], v178 offset:53248
	ds_read_b64_tr_b16 v[138:139], v179 offset:55296
	v_mfma_f32_32x32x16_bf16 v[32:47], v[228:231], v[208:211], v[32:47]
	v_exp_f32_e32 v109, v109
	v_exp_f32_e32 v110, v110
	v_exp_f32_e32 v111, v111
	ds_read_b64_tr_b16 v[144:145], v174 offset:57344
	ds_read_b64_tr_b16 v[146:147], v175 offset:59392
	v_mfma_f32_32x32x16_bf16 v[16:31], v[232:235], v[208:211], v[16:31]
	v_cvt_pk_bf16_f32 v212, v104, v105
	v_cvt_pk_bf16_f32 v213, v106, v107
	v_cvt_pk_bf16_f32 v214, v108, v109
	v_cvt_pk_bf16_f32 v215, v110, v111
	v_add_f32_e32 v187, v96, v187
	v_add_f32_e32 v192, v97, v192
	ds_read_b64_tr_b16 v[148:149], v176 offset:57344
	ds_read_b64_tr_b16 v[150:151], v177 offset:59392
	v_mfma_f32_32x32x16_bf16 v[0:15], v[236:239], v[208:211], v[0:15]
	v_add_f32_e32 v193, v98, v193
	v_add_f32_e32 v194, v99, v194
	v_add_f32_e32 v187, v100, v187
	v_add_f32_e32 v192, v101, v192
	v_add_f32_e32 v193, v102, v193
	v_add_f32_e32 v194, v103, v194
	ds_read_b64_tr_b16 v[152:153], v178 offset:57344
	ds_read_b64_tr_b16 v[154:155], v179 offset:59392
	s_waitcnt lgkmcnt(6)
	v_mfma_f32_32x32x16_bf16 v[48:63], v[128:131], v[212:215], v[48:63]
	v_exp_f32_e32 v80, v80
	v_exp_f32_e32 v81, v81
	v_exp_f32_e32 v82, v82
	ds_read_b64_tr_b16 v[240:241], v183 offset:57344
	ds_read_b64_tr_b16 v[242:243], v184 offset:59392
	ds_read_b128 v[128:131], v188 offset:8192
	v_mfma_f32_32x32x16_bf16 v[32:47], v[132:135], v[212:215], v[32:47]
	v_exp_f32_e32 v83, v83
	v_exp_f32_e32 v84, v84
	v_exp_f32_e32 v85, v85
	ds_read_b64_tr_b16 v[196:197], v174 offset:61440
	ds_read_b64_tr_b16 v[198:199], v175 offset:63488
	ds_read_b128 v[132:135], v189
	v_mfma_f32_32x32x16_bf16 v[16:31], v[136:139], v[212:215], v[16:31]
	v_exp_f32_e32 v86, v86
	v_exp_f32_e32 v87, v87
	v_cvt_pk_bf16_f32 v216, v80, v81
	v_cvt_pk_bf16_f32 v217, v82, v83
	ds_read_b64_tr_b16 v[200:201], v176 offset:61440
	ds_read_b64_tr_b16 v[202:203], v177 offset:63488
	ds_read_b128 v[136:139], v189 offset:8192
	v_mfma_f32_32x32x16_bf16 v[0:15], v[140:143], v[212:215], v[0:15]
	v_cvt_pk_bf16_f32 v218, v84, v85
	v_cvt_pk_bf16_f32 v219, v86, v87
	v_add_f32_e32 v187, v104, v187
	v_add_f32_e32 v192, v105, v192
	v_add_f32_e32 v193, v106, v193
	v_add_f32_e32 v194, v107, v194
	s_waitcnt lgkmcnt(12)
	ds_read_b64_tr_b16 v[204:205], v178 offset:61440
	ds_read_b64_tr_b16 v[206:207], v179 offset:63488
	ds_read_b128 v[140:143], v190
	s_waitcnt lgkmcnt(10)
	v_mfma_f32_32x32x16_bf16 v[48:63], v[144:147], v[216:219], v[48:63]
	v_exp_f32_e32 v88, v88
	v_exp_f32_e32 v89, v89
	v_exp_f32_e32 v90, v90
	ds_read_b64_tr_b16 v[246:247], v183 offset:61440
	ds_read_b64_tr_b16 v[248:249], v184 offset:63488
	ds_read_b128 v[144:147], v190 offset:8192
	v_mfma_f32_32x32x16_bf16 v[32:47], v[148:151], v[216:219], v[32:47]
	v_exp_f32_e32 v91, v91
	v_exp_f32_e32 v92, v92
	v_exp_f32_e32 v93, v93
	ds_read_b128 v[148:151], v191
	v_mfma_f32_32x32x16_bf16 v[16:31], v[152:155], v[216:219], v[16:31]
	v_exp_f32_e32 v94, v94
	v_exp_f32_e32 v95, v95
	v_cvt_pk_bf16_f32 v220, v88, v89
	v_cvt_pk_bf16_f32 v221, v90, v91
	ds_read_b128 v[152:155], v191 offset:8192
	v_mfma_f32_32x32x16_bf16 v[0:15], v[240:243], v[216:219], v[0:15]
	v_cvt_pk_bf16_f32 v222, v92, v93
	v_cvt_pk_bf16_f32 v223, v94, v95
	v_add_f32_e32 v187, v80, v187
	v_add_f32_e32 v192, v81, v192
	v_add_f32_e32 v193, v82, v193
	v_add_f32_e32 v194, v83, v194
	s_waitcnt lgkmcnt(3)
	v_mfma_f32_32x32x16_bf16 v[48:63], v[196:199], v[220:223], v[48:63]
	v_add_f32_e32 v187, v108, v187
	v_add_f32_e32 v192, v109, v192
	v_add_f32_e32 v193, v110, v193
	v_add_f32_e32 v194, v111, v194
	v_add_f32_e32 v187, v84, v187
	v_add_f32_e32 v192, v85, v192
	ds_read_b128 v[80:83], v188
	ds_read_b64_tr_b16 v[224:225], v174
	ds_read_b64_tr_b16 v[226:227], v175 offset:2048
	v_mfma_f32_32x32x16_bf16 v[32:47], v[200:203], v[220:223], v[32:47]
	v_add_f32_e32 v193, v86, v193
	v_add_f32_e32 v194, v87, v194
	v_add_f32_e32 v187, v88, v187
	v_add_f32_e32 v192, v89, v192
	v_add_f32_e32 v193, v90, v193
	v_add_f32_e32 v194, v91, v194
	ds_read_b64_tr_b16 v[228:229], v176
	ds_read_b64_tr_b16 v[230:231], v177 offset:2048
	v_mfma_f32_32x32x16_bf16 v[16:31], v[204:207], v[220:223], v[16:31]
	v_add_f32_e32 v187, v92, v187
	v_add_f32_e32 v192, v93, v192
	v_add_f32_e32 v193, v94, v193
	v_add_f32_e32 v194, v95, v194
	ds_read_b64_tr_b16 v[232:233], v178
	ds_read_b64_tr_b16 v[234:235], v179 offset:2048
	v_mfma_f32_32x32x16_bf16 v[0:15], v[246:249], v[220:223], v[0:15]
	ds_read_b64_tr_b16 v[236:237], v183
	ds_read_b64_tr_b16 v[238:239], v184 offset:2048
	s_add_i32 s68, s68, 4
	s_cmp_ge_u32 s69, s42
	s_barrier
	s_cbranch_scc0 .LBB0_927
	s_branch .Lattn_join
; __device__ __forceinline__ void glds16x4(const void* k0, const void* k1, const void* v0, const void* v1, unsigned voff, unsigned lk0, unsigned lk1, unsigned lv0, unsigned lv1) { unsigned keep;
;     asm volatile("s_mov_b32 %0, m0\n\t"
;                  "s_mov_b32 m0, %6\n\ts_nop 0\n\tglobal_load_lds_dwordx4 %1, %2\n\t"
;                  "s_mov_b32 m0, %7\n\ts_nop 0\n\tglobal_load_lds_dwordx4 %1, %3\n\t"
;                  "s_mov_b32 m0, %8\n\ts_nop 0\n\tglobal_load_lds_dwordx4 %1, %4\n\t"
;                  "s_mov_b32 m0, %9\n\ts_nop 0\n\tglobal_load_lds_dwordx4 %1, %5\n\t"
;                  "s_mov_b32 m0, %0"
;                  : "=&s"(keep) : "v"(voff), "s"(k0), "s"(k1), "s"(v0), "s"(v1), "s"(lk0), "s"(lk1), "s"(lv0), "s"(lv1) : "memory"); }
.Lattn_G:
.LG_loop:
	s_add_i32 s69, s68, -3
	s_mov_b32 m0, s53
	v_mfma_f32_32x32x16_bf16 v[96:111], v[132:135], v[116:119], v[64:79]
	global_load_lds_dwordx4 v163, s[4:5]
	s_mov_b32 m0, s58
	v_mfma_f32_32x32x16_bf16 v[96:111], v[140:143], v[120:123], v[96:111]
	global_load_lds_dwordx4 v254, s[4:5]
	s_mov_b32 m0, s25
	s_waitcnt lgkmcnt(10)
	v_mfma_f32_32x32x16_bf16 v[96:111], v[148:151], v[124:127], v[96:111]
	global_load_lds_dwordx4 v255, s[4:5]
	ds_read_b64_tr_b16 v[132:133], v176 offset:4096
	ds_read_b64_tr_b16 v[134:135], v177 offset:6144
	s_mov_b32 m0, s63
	s_waitcnt lgkmcnt(10)
	v_mfma_f32_32x32x16_bf16 v[96:111], v[80:83], v[112:115], v[96:111]
	global_load_lds_dwordx4 v253, s[4:5]
	ds_read_b64_tr_b16 v[140:141], v183 offset:4096
	ds_read_b64_tr_b16 v[142:143], v184 offset:6144
	s_add_i32 m0, s53, 0xfffff000
	v_mfma_f32_32x32x16_bf16 v[80:95], v[128:131], v[112:115], v[64:79]
	global_load_lds_dwordx4 v250, s[4:5]
	ds_read_b64_tr_b16 v[128:129], v174 offset:4096
	ds_read_b64_tr_b16 v[130:131], v175 offset:6144
	s_add_i32 m0, s58, 0xfffff000
	v_mfma_f32_32x32x16_bf16 v[80:95], v[136:139], v[116:119], v[80:95]
	global_load_lds_dwordx4 v251, s[4:5]
	s_nop 1
	s_add_i32 m0, s25, 0xfffff000
	v_mfma_f32_32x32x16_bf16 v[80:95], v[144:147], v[120:123], v[80:95]
	global_load_lds_dwordx4 v252, s[4:5]
	v_exp_f32_e32 v96, v96
	v_exp_f32_e32 v97, v97
	v_exp_f32_e32 v98, v98
	s_add_i32 m0, s63, 0xfffff000
	v_mfma_f32_32x32x16_bf16 v[80:95], v[152:155], v[124:127], v[80:95]
	global_load_lds_dwordx4 v195, s[4:5]
	v_exp_f32_e32 v99, v99
	v_exp_f32_e32 v100, v100
	v_exp_f32_e32 v101, v101
	v_exp_f32_e32 v102, v102
	v_exp_f32_e32 v103, v103
	v_cvt_pk_bf16_f32 v208, v96, v97
	v_cvt_pk_bf16_f32 v209, v98, v99
	v_cvt_pk_bf16_f32 v210, v100, v101
	v_cvt_pk_bf16_f32 v211, v102, v103
	v_exp_f32_e32 v104, v104
	v_exp_f32_e32 v105, v105
	s_waitcnt lgkmcnt(6)
	v_mfma_f32_32x32x16_bf16 v[48:63], v[224:227], v[208:211], v[48:63]
	v_exp_f32_e32 v106, v106
	v_exp_f32_e32 v107, v107
	v_exp_f32_e32 v108, v108
	ds_read_b64_tr_b16 v[136:137], v178 offset:4096
	ds_read_b64_tr_b16 v[138:139], v179 offset:6144
	v_mfma_f32_32x32x16_bf16 v[32:47], v[228:231], v[208:211], v[32:47]
	v_exp_f32_e32 v109, v109
	v_exp_f32_e32 v110, v110
	v_exp_f32_e32 v111, v111
	ds_read_b64_tr_b16 v[144:145], v174 offset:8192
	ds_read_b64_tr_b16 v[146:147], v175 offset:10240
	v_mfma_f32_32x32x16_bf16 v[16:31], v[232:235], v[208:211], v[16:31]
	v_cvt_pk_bf16_f32 v212, v104, v105
	v_cvt_pk_bf16_f32 v213, v106, v107
	v_cvt_pk_bf16_f32 v214, v108, v109
	v_cvt_pk_bf16_f32 v215, v110, v111
	v_add_f32_e32 v187, v96, v187
	v_add_f32_e32 v192, v97, v192
	ds_read_b64_tr_b16 v[148:149], v176 offset:8192
	ds_read_b64_tr_b16 v[150:151], v177 offset:10240
	v_mfma_f32_32x32x16_bf16 v[0:15], v[236:239], v[208:211], v[0:15]
	v_add_f32_e32 v193, v98, v193
	v_add_f32_e32 v194, v99, v194
	v_add_f32_e32 v187, v100, v187
	v_add_f32_e32 v192, v101, v192
	v_add_f32_e32 v193, v102, v193
	v_add_f32_e32 v194, v103, v194
	ds_read_b64_tr_b16 v[152:153], v178 offset:8192
	ds_read_b64_tr_b16 v[154:155], v179 offset:10240
	s_waitcnt lgkmcnt(6)
	v_mfma_f32_32x32x16_bf16 v[48:63], v[128:131], v[212:215], v[48:63]
	v_exp_f32_e32 v80, v80
	v_exp_f32_e32 v81, v81
	v_exp_f32_e32 v82, v82
	ds_read_b64_tr_b16 v[240:241], v183 offset:8192
	ds_read_b64_tr_b16 v[242:243], v184 offset:10240
	ds_read_b128 v[128:131], v188 offset:24576
	v_mfma_f32_32x32x16_bf16 v[32:47], v[132:135], v[212:215], v[32:47]
	v_exp_f32_e32 v83, v83
	v_exp_f32_e32 v84, v84
	v_exp_f32_e32 v85, v85
	ds_read_b64_tr_b16 v[196:197], v174 offset:12288
	ds_read_b64_tr_b16 v[198:199], v175 offset:14336
	ds_read_b128 v[132:135], v189 offset:16384
	v_mfma_f32_32x32x16_bf16 v[16:31], v[136:139], v[212:215], v[16:31]
	v_exp_f32_e32 v86, v86
	v_exp_f32_e32 v87, v87
	v_cvt_pk_bf16_f32 v216, v80, v81
	v_cvt_pk_bf16_f32 v217, v82, v83
	ds_read_b64_tr_b16 v[200:201], v176 offset:12288
	ds_read_b64_tr_b16 v[202:203], v177 offset:14336
	ds_read_b128 v[136:139], v189 offset:24576
	v_mfma_f32_32x32x16_bf16 v[0:15], v[140:143], v[212:215], v[0:15]
	v_cvt_pk_bf16_f32 v218, v84, v85
	v_cvt_pk_bf16_f32 v219, v86, v87
	v_add_f32_e32 v187, v104, v187
	v_add_f32_e32 v192, v105, v192
	v_add_f32_e32 v193, v106, v193
	v_add_f32_e32 v194, v107, v194
	s_waitcnt lgkmcnt(12)
	ds_read_b64_tr_b16 v[204:205], v178 offset:12288
	ds_read_b64_tr_b16 v[206:207], v179 offset:14336
	ds_read_b128 v[140:143], v190 offset:16384
	s_waitcnt lgkmcnt(10)
	v_mfma_f32_32x32x16_bf16 v[48:63], v[144:147], v[216:219], v[48:63]
	v_exp_f32_e32 v88, v88
	v_exp_f32_e32 v89, v89
	v_exp_f32_e32 v90, v90
	ds_read_b64_tr_b16 v[246:247], v183 offset:12288
	ds_read_b64_tr_b16 v[248:249], v184 offset:14336
	ds_read_b128 v[144:147], v190 offset:24576
	v_mfma_f32_32x32x16_bf16 v[32:47], v[148:151], v[216:219], v[32:47]
	v_exp_f32_e32 v91, v91
	v_exp_f32_e32 v92, v92
	v_exp_f32_e32 v93, v93
	ds_read_b128 v[148:151], v191 offset:16384
	v_mfma_f32_32x32x16_bf16 v[16:31], v[152:155], v[216:219], v[16:31]
	v_exp_f32_e32 v94, v94
	v_exp_f32_e32 v95, v95
	v_cvt_pk_bf16_f32 v220, v88, v89
	v_cvt_pk_bf16_f32 v221, v90, v91
	ds_read_b128 v[152:155], v191 offset:24576
	v_mfma_f32_32x32x16_bf16 v[0:15], v[240:243], v[216:219], v[0:15]
	v_cvt_pk_bf16_f32 v222, v92, v93
	v_cvt_pk_bf16_f32 v223, v94, v95
	v_add_f32_e32 v187, v80, v187
	v_add_f32_e32 v192, v81, v192
	v_add_f32_e32 v193, v82, v193
	v_add_f32_e32 v194, v83, v194
	s_waitcnt lgkmcnt(3)
	v_mfma_f32_32x32x16_bf16 v[48:63], v[196:199], v[220:223], v[48:63]
	v_add_f32_e32 v187, v108, v187
	v_add_f32_e32 v192, v109, v192
	v_add_f32_e32 v193, v110, v193
	v_add_f32_e32 v194, v111, v194
	v_add_f32_e32 v187, v84, v187
	v_add_f32_e32 v192, v85, v192
	ds_read_b128 v[80:83], v188 offset:16384
	ds_read_b64_tr_b16 v[224:225], v174 offset:16384
	ds_read_b64_tr_b16 v[226:227], v175 offset:18432
	v_mfma_f32_32x32x16_bf16 v[32:47], v[200:203], v[220:223], v[32:47]
	v_add_f32_e32 v193, v86, v193
	v_add_f32_e32 v194, v87, v194
	v_add_f32_e32 v187, v88, v187
	v_add_f32_e32 v192, v89, v192
	v_add_f32_e32 v193, v90, v193
	v_add_f32_e32 v194, v91, v194
	ds_read_b64_tr_b16 v[228:229], v176 offset:16384
	ds_read_b64_tr_b16 v[230:231], v177 offset:18432
	v_mfma_f32_32x32x16_bf16 v[16:31], v[204:207], v[220:223], v[16:31]
	v_add_f32_e32 v187, v92, v187
	v_add_f32_e32 v192, v93, v192
	v_add_f32_e32 v193, v94, v193
	v_add_f32_e32 v194, v95, v194
	ds_read_b64_tr_b16 v[232:233], v178 offset:16384
	ds_read_b64_tr_b16 v[234:235], v179 offset:18432
	v_mfma_f32_32x32x16_bf16 v[0:15], v[246:249], v[220:223], v[0:15]
	ds_read_b64_tr_b16 v[236:237], v183 offset:16384
	ds_read_b64_tr_b16 v[238:239], v184 offset:18432
	s_add_i32 s10, s68, -3
	s_min_u32 s10, s10, s24
	s_lshl_b32 s10, s10, 15
	s_add_u32 s22, s20, s10
	s_addc_u32 s23, s21, 0
	s_waitcnt vmcnt(8)
	s_barrier
; __device__ __forceinline__ void glds16x4(const void* k0, const void* k1, const void* v0, const void* v1, unsigned voff, unsigned lk0, unsigned lk1, unsigned lv0, unsigned lv1) { unsigned keep;
;     asm volatile("s_mov_b32 %0, m0\n\t"
;                  "s_mov_b32 m0, %6\n\ts_nop 0\n\tglobal_load_lds_dwordx4 %1, %2\n\t"
;                  "s_mov_b32 m0, %7\n\ts_nop 0\n\tglobal_load_lds_dwordx4 %1, %3\n\t"
;                  "s_mov_b32 m0, %8\n\ts_nop 0\n\tglobal_load_lds_dwordx4 %1, %4\n\t"
;                  "s_mov_b32 m0, %9\n\ts_nop 0\n\tglobal_load_lds_dwordx4 %1, %5\n\t"
;                  "s_mov_b32 m0, %0"
;                  : "=&s"(keep) : "v"(voff), "s"(k0), "s"(k1), "s"(v0), "s"(v1), "s"(lk0), "s"(lk1), "s"(lv0), "s"(lv1) : "memory"); }
	s_mov_b32 m0, s43
	v_mfma_f32_32x32x16_bf16 v[96:111], v[132:135], v[116:119], v[64:79]
	global_load_lds_dwordx4 v163, s[22:23]
	s_mov_b32 m0, s45
	v_mfma_f32_32x32x16_bf16 v[96:111], v[140:143], v[120:123], v[96:111]
	global_load_lds_dwordx4 v254, s[22:23]
	s_mov_b32 m0, s44
	s_waitcnt lgkmcnt(10)
	v_mfma_f32_32x32x16_bf16 v[96:111], v[148:151], v[124:127], v[96:111]
	global_load_lds_dwordx4 v255, s[22:23]
	ds_read_b64_tr_b16 v[132:133], v176 offset:20480
	ds_read_b64_tr_b16 v[134:135], v177 offset:22528
	s_mov_b32 m0, s48
	s_waitcnt lgkmcnt(10)
	v_mfma_f32_32x32x16_bf16 v[96:111], v[80:83], v[112:115], v[96:111]
	global_load_lds_dwordx4 v253, s[22:23]
	ds_read_b64_tr_b16 v[140:141], v183 offset:20480
	ds_read_b64_tr_b16 v[142:143], v184 offset:22528
	s_add_i32 m0, s43, 0xfffff000
	v_mfma_f32_32x32x16_bf16 v[80:95], v[128:131], v[112:115], v[64:79]
	global_load_lds_dwordx4 v250, s[22:23]
	ds_read_b64_tr_b16 v[128:129], v174 offset:20480
	ds_read_b64_tr_b16 v[130:131], v175 offset:22528
	s_add_i32 m0, s45, 0xfffff000
	v_mfma_f32_32x32x16_bf16 v[80:95], v[136:139], v[116:119], v[80:95]
	global_load_lds_dwordx4 v251, s[22:23]
	s_nop 1
	s_add_i32 m0, s44, 0xfffff000
	v_mfma_f32_32x32x16_bf16 v[80:95], v[144:147], v[120:123], v[80:95]
	global_load_lds_dwordx4 v252, s[22:23]
	v_exp_f32_e32 v96, v96
	v_exp_f32_e32 v97, v97
	v_exp_f32_e32 v98, v98
	s_add_i32 m0, s48, 0xfffff000
	v_mfma_f32_32x32x16_bf16 v[80:95], v[152:155], v[124:127], v[80:95]
	global_load_lds_dwordx4 v195, s[22:23]
	v_exp_f32_e32 v99, v99
	v_exp_f32_e32 v100, v100
	v_exp_f32_e32 v101, v101
	v_exp_f32_e32 v102, v102
	v_exp_f32_e32 v103, v103
	v_cvt_pk_bf16_f32 v208, v96, v97
	v_cvt_pk_bf16_f32 v209, v98, v99
	v_cvt_pk_bf16_f32 v210, v100, v101
	v_cvt_pk_bf16_f32 v211, v102, v103
	v_exp_f32_e32 v104, v104
	v_exp_f32_e32 v105, v105
	s_waitcnt lgkmcnt(6)
	v_mfma_f32_32x32x16_bf16 v[48:63], v[224:227], v[208:211], v[48:63]
	v_exp_f32_e32 v106, v106
	v_exp_f32_e32 v107, v107
	v_exp_f32_e32 v108, v108
	ds_read_b64_tr_b16 v[136:137], v178 offset:20480
	ds_read_b64_tr_b16 v[138:139], v179 offset:22528
	v_mfma_f32_32x32x16_bf16 v[32:47], v[228:231], v[208:211], v[32:47]
	v_exp_f32_e32 v109, v109
	v_exp_f32_e32 v110, v110
	v_exp_f32_e32 v111, v111
	ds_read_b64_tr_b16 v[144:145], v174 offset:24576
	ds_read_b64_tr_b16 v[146:147], v175 offset:26624
	v_mfma_f32_32x32x16_bf16 v[16:31], v[232:235], v[208:211], v[16:31]
	v_cvt_pk_bf16_f32 v212, v104, v105
	v_cvt_pk_bf16_f32 v213, v106, v107
	v_cvt_pk_bf16_f32 v214, v108, v109
	v_cvt_pk_bf16_f32 v215, v110, v111
	v_add_f32_e32 v187, v96, v187
	v_add_f32_e32 v192, v97, v192
	ds_read_b64_tr_b16 v[148:149], v176 offset:24576
	ds_read_b64_tr_b16 v[150:151], v177 offset:26624
	v_mfma_f32_32x32x16_bf16 v[0:15], v[236:239], v[208:211], v[0:15]
	v_add_f32_e32 v193, v98, v193
	v_add_f32_e32 v194, v99, v194
	v_add_f32_e32 v187, v100, v187
	v_add_f32_e32 v192, v101, v192
	v_add_f32_e32 v193, v102, v193
	v_add_f32_e32 v194, v103, v194
	ds_read_b64_tr_b16 v[152:153], v178 offset:24576
	ds_read_b64_tr_b16 v[154:155], v179 offset:26624
	s_waitcnt lgkmcnt(6)
	v_mfma_f32_32x32x16_bf16 v[48:63], v[128:131], v[212:215], v[48:63]
	v_exp_f32_e32 v80, v80
	v_exp_f32_e32 v81, v81
	v_exp_f32_e32 v82, v82
	ds_read_b64_tr_b16 v[240:241], v183 offset:24576
	ds_read_b64_tr_b16 v[242:243], v184 offset:26624
	ds_read_b128 v[128:131], v188 offset:40960
	v_mfma_f32_32x32x16_bf16 v[32:47], v[132:135], v[212:215], v[32:47]
	v_exp_f32_e32 v83, v83
	v_exp_f32_e32 v84, v84
	v_exp_f32_e32 v85, v85
	ds_read_b64_tr_b16 v[196:197], v174 offset:28672
	ds_read_b64_tr_b16 v[198:199], v175 offset:30720
	ds_read_b128 v[132:135], v189 offset:32768
	v_mfma_f32_32x32x16_bf16 v[16:31], v[136:139], v[212:215], v[16:31]
	v_exp_f32_e32 v86, v86
	v_exp_f32_e32 v87, v87
	v_cvt_pk_bf16_f32 v216, v80, v81
	v_cvt_pk_bf16_f32 v217, v82, v83
	ds_read_b64_tr_b16 v[200:201], v176 offset:28672
	ds_read_b64_tr_b16 v[202:203], v177 offset:30720
	ds_read_b128 v[136:139], v189 offset:40960
	v_mfma_f32_32x32x16_bf16 v[0:15], v[140:143], v[212:215], v[0:15]
	v_cvt_pk_bf16_f32 v218, v84, v85
	v_cvt_pk_bf16_f32 v219, v86, v87
	v_add_f32_e32 v187, v104, v187
	v_add_f32_e32 v192, v105, v192
	v_add_f32_e32 v193, v106, v193
	v_add_f32_e32 v194, v107, v194
	s_waitcnt lgkmcnt(12)
	ds_read_b64_tr_b16 v[204:205], v178 offset:28672
	ds_read_b64_tr_b16 v[206:207], v179 offset:30720
	ds_read_b128 v[140:143], v190 offset:32768
	s_waitcnt lgkmcnt(10)
	v_mfma_f32_32x32x16_bf16 v[48:63], v[144:147], v[216:219], v[48:63]
	v_exp_f32_e32 v88, v88
	v_exp_f32_e32 v89, v89
	v_exp_f32_e32 v90, v90
	ds_read_b64_tr_b16 v[246:247], v183 offset:28672
	ds_read_b64_tr_b16 v[248:249], v184 offset:30720
	ds_read_b128 v[144:147], v190 offset:40960
	v_mfma_f32_32x32x16_bf16 v[32:47], v[148:151], v[216:219], v[32:47]
	v_exp_f32_e32 v91, v91
	v_exp_f32_e32 v92, v92
	v_exp_f32_e32 v93, v93
	ds_read_b128 v[148:151], v191 offset:32768
	v_mfma_f32_32x32x16_bf16 v[16:31], v[152:155], v[216:219], v[16:31]
	v_exp_f32_e32 v94, v94
	v_exp_f32_e32 v95, v95
	v_cvt_pk_bf16_f32 v220, v88, v89
	v_cvt_pk_bf16_f32 v221, v90, v91
	ds_read_b128 v[152:155], v191 offset:40960
	v_mfma_f32_32x32x16_bf16 v[0:15], v[240:243], v[216:219], v[0:15]
	v_cvt_pk_bf16_f32 v222, v92, v93
	v_cvt_pk_bf16_f32 v223, v94, v95
	v_add_f32_e32 v187, v80, v187
	v_add_f32_e32 v192, v81, v192
	v_add_f32_e32 v193, v82, v193
	v_add_f32_e32 v194, v83, v194
	s_waitcnt lgkmcnt(3)
	v_mfma_f32_32x32x16_bf16 v[48:63], v[196:199], v[220:223], v[48:63]
	v_add_f32_e32 v187, v108, v187
	v_add_f32_e32 v192, v109, v192
	v_add_f32_e32 v193, v110, v193
	v_add_f32_e32 v194, v111, v194
	v_add_f32_e32 v187, v84, v187
	v_add_f32_e32 v192, v85, v192
	ds_read_b128 v[80:83], v188 offset:32768
	ds_read_b64_tr_b16 v[224:225], v174 offset:32768
	ds_read_b64_tr_b16 v[226:227], v175 offset:34816
	v_mfma_f32_32x32x16_bf16 v[32:47], v[200:203], v[220:223], v[32:47]
	v_add_f32_e32 v193, v86, v193
	v_add_f32_e32 v194, v87, v194
	v_add_f32_e32 v187, v88, v187
	v_add_f32_e32 v192, v89, v192
	v_add_f32_e32 v193, v90, v193
	v_add_f32_e32 v194, v91, v194
	ds_read_b64_tr_b16 v[228:229], v176 offset:32768
	ds_read_b64_tr_b16 v[230:231], v177 offset:34816
	v_mfma_f32_32x32x16_bf16 v[16:31], v[204:207], v[220:223], v[16:31]
	v_add_f32_e32 v187, v92, v187
	v_add_f32_e32 v192, v93, v192
	v_add_f32_e32 v193, v94, v193
	v_add_f32_e32 v194, v95, v194
	ds_read_b64_tr_b16 v[232:233], v178 offset:32768
	ds_read_b64_tr_b16 v[234:235], v179 offset:34816
	v_mfma_f32_32x32x16_bf16 v[0:15], v[246:249], v[220:223], v[0:15]
	ds_read_b64_tr_b16 v[236:237], v183 offset:32768
	ds_read_b64_tr_b16 v[238:239], v184 offset:34816
	s_add_i32 s10, s68, -2
	s_min_u32 s10, s10, s24
	s_lshl_b32 s10, s10, 15
	s_add_u32 s4, s20, s10
	s_addc_u32 s5, s21, 0
	s_waitcnt vmcnt(8)
	s_barrier
; __device__ __forceinline__ void glds16x4(const void* k0, const void* k1, const void* v0, const void* v1, unsigned voff, unsigned lk0, unsigned lk1, unsigned lv0, unsigned lv1) { unsigned keep;
;     asm volatile("s_mov_b32 %0, m0\n\t"
;                  "s_mov_b32 m0, %6\n\ts_nop 0\n\tglobal_load_lds_dwordx4 %1, %2\n\t"
;                  "s_mov_b32 m0, %7\n\ts_nop 0\n\tglobal_load_lds_dwordx4 %1, %3\n\t"
;                  "s_mov_b32 m0, %8\n\ts_nop 0\n\tglobal_load_lds_dwordx4 %1, %4\n\t"
;                  "s_mov_b32 m0, %9\n\ts_nop 0\n\tglobal_load_lds_dwordx4 %1, %5\n\t"
;                  "s_mov_b32 m0, %0"
;                  : "=&s"(keep) : "v"(voff), "s"(k0), "s"(k1), "s"(v0), "s"(v1), "s"(lk0), "s"(lk1), "s"(lv0), "s"(lv1) : "memory"); }
	s_mov_b32 m0, s46
	v_mfma_f32_32x32x16_bf16 v[96:111], v[132:135], v[116:119], v[64:79]
	global_load_lds_dwordx4 v163, s[4:5]
	s_mov_b32 m0, s47
	v_mfma_f32_32x32x16_bf16 v[96:111], v[140:143], v[120:123], v[96:111]
	global_load_lds_dwordx4 v254, s[4:5]
	s_mov_b32 m0, s51
	s_waitcnt lgkmcnt(10)
	v_mfma_f32_32x32x16_bf16 v[96:111], v[148:151], v[124:127], v[96:111]
	global_load_lds_dwordx4 v255, s[4:5]
	ds_read_b64_tr_b16 v[132:133], v176 offset:36864
	ds_read_b64_tr_b16 v[134:135], v177 offset:38912
	s_mov_b32 m0, s52
	s_waitcnt lgkmcnt(10)
	v_mfma_f32_32x32x16_bf16 v[96:111], v[80:83], v[112:115], v[96:111]
	global_load_lds_dwordx4 v253, s[4:5]
	ds_read_b64_tr_b16 v[140:141], v183 offset:36864
	ds_read_b64_tr_b16 v[142:143], v184 offset:38912
	s_add_i32 m0, s46, 0xfffff000
	v_mfma_f32_32x32x16_bf16 v[80:95], v[128:131], v[112:115], v[64:79]
	global_load_lds_dwordx4 v250, s[4:5]
	ds_read_b64_tr_b16 v[128:129], v174 offset:36864
	ds_read_b64_tr_b16 v[130:131], v175 offset:38912
	s_add_i32 m0, s47, 0xfffff000
	v_mfma_f32_32x32x16_bf16 v[80:95], v[136:139], v[116:119], v[80:95]
	global_load_lds_dwordx4 v251, s[4:5]
	s_nop 1
	s_add_i32 m0, s51, 0xfffff000
	v_mfma_f32_32x32x16_bf16 v[80:95], v[144:147], v[120:123], v[80:95]
	global_load_lds_dwordx4 v252, s[4:5]
	v_exp_f32_e32 v96, v96
	v_exp_f32_e32 v97, v97
	v_exp_f32_e32 v98, v98
	s_add_i32 m0, s52, 0xfffff000
	v_mfma_f32_32x32x16_bf16 v[80:95], v[152:155], v[124:127], v[80:95]
	global_load_lds_dwordx4 v195, s[4:5]
	v_exp_f32_e32 v99, v99
	v_exp_f32_e32 v100, v100
	v_exp_f32_e32 v101, v101
	v_exp_f32_e32 v102, v102
	v_exp_f32_e32 v103, v103
	v_cvt_pk_bf16_f32 v208, v96, v97
	v_cvt_pk_bf16_f32 v209, v98, v99
	v_cvt_pk_bf16_f32 v210, v100, v101
	v_cvt_pk_bf16_f32 v211, v102, v103
	v_exp_f32_e32 v104, v104
	v_exp_f32_e32 v105, v105
	s_waitcnt lgkmcnt(6)
	v_mfma_f32_32x32x16_bf16 v[48:63], v[224:227], v[208:211], v[48:63]
	v_exp_f32_e32 v106, v106
	v_exp_f32_e32 v107, v107
	v_exp_f32_e32 v108, v108
	ds_read_b64_tr_b16 v[136:137], v178 offset:36864
	ds_read_b64_tr_b16 v[138:139], v179 offset:38912
	v_mfma_f32_32x32x16_bf16 v[32:47], v[228:231], v[208:211], v[32:47]
	v_exp_f32_e32 v109, v109
	v_exp_f32_e32 v110, v110
	v_exp_f32_e32 v111, v111
	ds_read_b64_tr_b16 v[144:145], v174 offset:40960
	ds_read_b64_tr_b16 v[146:147], v175 offset:43008
	v_mfma_f32_32x32x16_bf16 v[16:31], v[232:235], v[208:211], v[16:31]
	v_cvt_pk_bf16_f32 v212, v104, v105
	v_cvt_pk_bf16_f32 v213, v106, v107
	v_cvt_pk_bf16_f32 v214, v108, v109
	v_cvt_pk_bf16_f32 v215, v110, v111
	v_add_f32_e32 v187, v96, v187
	v_add_f32_e32 v192, v97, v192
	ds_read_b64_tr_b16 v[148:149], v176 offset:40960
	ds_read_b64_tr_b16 v[150:151], v177 offset:43008
	v_mfma_f32_32x32x16_bf16 v[0:15], v[236:239], v[208:211], v[0:15]
	v_add_f32_e32 v193, v98, v193
	v_add_f32_e32 v194, v99, v194
	v_add_f32_e32 v187, v100, v187
	v_add_f32_e32 v192, v101, v192
	v_add_f32_e32 v193, v102, v193
	v_add_f32_e32 v194, v103, v194
	ds_read_b64_tr_b16 v[152:153], v178 offset:40960
	ds_read_b64_tr_b16 v[154:155], v179 offset:43008
	s_waitcnt lgkmcnt(6)
	v_mfma_f32_32x32x16_bf16 v[48:63], v[128:131], v[212:215], v[48:63]
	v_exp_f32_e32 v80, v80
	v_exp_f32_e32 v81, v81
	v_exp_f32_e32 v82, v82
	ds_read_b64_tr_b16 v[240:241], v183 offset:40960
	ds_read_b64_tr_b16 v[242:243], v184 offset:43008
	ds_read_b128 v[128:131], v188 offset:57344
	v_mfma_f32_32x32x16_bf16 v[32:47], v[132:135], v[212:215], v[32:47]
	v_exp_f32_e32 v83, v83
	v_exp_f32_e32 v84, v84
	v_exp_f32_e32 v85, v85
	ds_read_b64_tr_b16 v[196:197], v174 offset:45056
	ds_read_b64_tr_b16 v[198:199], v175 offset:47104
	ds_read_b128 v[132:135], v189 offset:49152
	v_mfma_f32_32x32x16_bf16 v[16:31], v[136:139], v[212:215], v[16:31]
	v_exp_f32_e32 v86, v86
	v_exp_f32_e32 v87, v87
	v_cvt_pk_bf16_f32 v216, v80, v81
	v_cvt_pk_bf16_f32 v217, v82, v83
	ds_read_b64_tr_b16 v[200:201], v176 offset:45056
	ds_read_b64_tr_b16 v[202:203], v177 offset:47104
	ds_read_b128 v[136:139], v189 offset:57344
	v_mfma_f32_32x32x16_bf16 v[0:15], v[140:143], v[212:215], v[0:15]
	v_cvt_pk_bf16_f32 v218, v84, v85
	v_cvt_pk_bf16_f32 v219, v86, v87
	v_add_f32_e32 v187, v104, v187
	v_add_f32_e32 v192, v105, v192
	v_add_f32_e32 v193, v106, v193
	v_add_f32_e32 v194, v107, v194
	s_waitcnt lgkmcnt(12)
	ds_read_b64_tr_b16 v[204:205], v178 offset:45056
	ds_read_b64_tr_b16 v[206:207], v179 offset:47104
	ds_read_b128 v[140:143], v190 offset:49152
	s_waitcnt lgkmcnt(10)
	v_mfma_f32_32x32x16_bf16 v[48:63], v[144:147], v[216:219], v[48:63]
	v_exp_f32_e32 v88, v88
	v_exp_f32_e32 v89, v89
	v_exp_f32_e32 v90, v90
	ds_read_b64_tr_b16 v[246:247], v183 offset:45056
	ds_read_b64_tr_b16 v[248:249], v184 offset:47104
	ds_read_b128 v[144:147], v190 offset:57344
	v_mfma_f32_32x32x16_bf16 v[32:47], v[148:151], v[216:219], v[32:47]
	v_exp_f32_e32 v91, v91
	v_exp_f32_e32 v92, v92
	v_exp_f32_e32 v93, v93
	ds_read_b128 v[148:151], v191 offset:49152
	v_mfma_f32_32x32x16_bf16 v[16:31], v[152:155], v[216:219], v[16:31]
	v_exp_f32_e32 v94, v94
	v_exp_f32_e32 v95, v95
	v_cvt_pk_bf16_f32 v220, v88, v89
	v_cvt_pk_bf16_f32 v221, v90, v91
	ds_read_b128 v[152:155], v191 offset:57344
	v_mfma_f32_32x32x16_bf16 v[0:15], v[240:243], v[216:219], v[0:15]
	v_cvt_pk_bf16_f32 v222, v92, v93
	v_cvt_pk_bf16_f32 v223, v94, v95
	v_add_f32_e32 v187, v80, v187
	v_add_f32_e32 v192, v81, v192
	v_add_f32_e32 v193, v82, v193
	v_add_f32_e32 v194, v83, v194
	s_waitcnt lgkmcnt(3)
	v_mfma_f32_32x32x16_bf16 v[48:63], v[196:199], v[220:223], v[48:63]
	v_add_f32_e32 v187, v108, v187
	v_add_f32_e32 v192, v109, v192
	v_add_f32_e32 v193, v110, v193
	v_add_f32_e32 v194, v111, v194
	v_add_f32_e32 v187, v84, v187
	v_add_f32_e32 v192, v85, v192
	ds_read_b128 v[80:83], v188 offset:49152
	ds_read_b64_tr_b16 v[224:225], v174 offset:49152
	ds_read_b64_tr_b16 v[226:227], v175 offset:51200
	v_mfma_f32_32x32x16_bf16 v[32:47], v[200:203], v[220:223], v[32:47]
	v_add_f32_e32 v193, v86, v193
	v_add_f32_e32 v194, v87, v194
	v_add_f32_e32 v187, v88, v187
	v_add_f32_e32 v192, v89, v192
	v_add_f32_e32 v193, v90, v193
	v_add_f32_e32 v194, v91, v194
	ds_read_b64_tr_b16 v[228:229], v176 offset:49152
	ds_read_b64_tr_b16 v[230:231], v177 offset:51200
	v_mfma_f32_32x32x16_bf16 v[16:31], v[204:207], v[220:223], v[16:31]
	v_add_f32_e32 v187, v92, v187
	v_add_f32_e32 v192, v93, v192
	v_add_f32_e32 v193, v94, v193
	v_add_f32_e32 v194, v95, v194
	ds_read_b64_tr_b16 v[232:233], v178 offset:49152
	ds_read_b64_tr_b16 v[234:235], v179 offset:51200
	v_mfma_f32_32x32x16_bf16 v[0:15], v[246:249], v[220:223], v[0:15]
	ds_read_b64_tr_b16 v[236:237], v183 offset:49152
	ds_read_b64_tr_b16 v[238:239], v184 offset:51200
	s_add_i32 s10, s68, -1
	s_min_u32 s10, s10, s24
	s_lshl_b32 s10, s10, 15
	s_add_u32 s22, s20, s10
	s_addc_u32 s23, s21, 0
	s_waitcnt vmcnt(8)
	s_barrier
; __device__ __forceinline__ void glds16x4(const void* k0, const void* k1, const void* v0, const void* v1, unsigned voff, unsigned lk0, unsigned lk1, unsigned lv0, unsigned lv1) { unsigned keep;
;     asm volatile("s_mov_b32 %0, m0\n\t"
;                  "s_mov_b32 m0, %6\n\ts_nop 0\n\tglobal_load_lds_dwordx4 %1, %2\n\t"
;                  "s_mov_b32 m0, %7\n\ts_nop 0\n\tglobal_load_lds_dwordx4 %1, %3\n\t"
;                  "s_mov_b32 m0, %8\n\ts_nop 0\n\tglobal_load_lds_dwordx4 %1, %4\n\t"
;                  "s_mov_b32 m0, %9\n\ts_nop 0\n\tglobal_load_lds_dwordx4 %1, %5\n\t"
;                  "s_mov_b32 m0, %0"
;                  : "=&s"(keep) : "v"(voff), "s"(k0), "s"(k1), "s"(v0), "s"(v1), "s"(lk0), "s"(lk1), "s"(lv0), "s"(lv1) : "memory"); }
; __device__ __forceinline__ void attn_unit(LAS unsigned char* L, bf16_t* QKV, size_t rowbase, int S, int h, int qb, float lam, const float* subln, unsigned* kmax) {
;     ...
;     for (int t = 0; t < NT; t += 4) { TILE(t, 0); TILE(t + 1, 1); TILE(t + 2, 2); TILE(t + 3, 3); }
	s_mov_b32 m0, s49
	v_mfma_f32_32x32x16_bf16 v[96:111], v[132:135], v[116:119], v[64:79]
	global_load_lds_dwordx4 v163, s[22:23]
	s_mov_b32 m0, s50
	v_mfma_f32_32x32x16_bf16 v[96:111], v[140:143], v[120:123], v[96:111]
	global_load_lds_dwordx4 v254, s[22:23]
	s_mov_b32 m0, s59
	s_waitcnt lgkmcnt(10)
	v_mfma_f32_32x32x16_bf16 v[96:111], v[148:151], v[124:127], v[96:111]
	global_load_lds_dwordx4 v255, s[22:23]
	ds_read_b64_tr_b16 v[132:133], v176 offset:53248
	ds_read_b64_tr_b16 v[134:135], v177 offset:55296
	s_mov_b32 m0, s61
	s_waitcnt lgkmcnt(10)
	v_mfma_f32_32x32x16_bf16 v[96:111], v[80:83], v[112:115], v[96:111]
	global_load_lds_dwordx4 v253, s[22:23]
	ds_read_b64_tr_b16 v[140:141], v183 offset:53248
	ds_read_b64_tr_b16 v[142:143], v184 offset:55296
	s_add_i32 m0, s49, 0xfffff000
	v_mfma_f32_32x32x16_bf16 v[80:95], v[128:131], v[112:115], v[64:79]
	global_load_lds_dwordx4 v250, s[22:23]
	ds_read_b64_tr_b16 v[128:129], v174 offset:53248
	ds_read_b64_tr_b16 v[130:131], v175 offset:55296
	s_add_i32 m0, s50, 0xfffff000
	v_mfma_f32_32x32x16_bf16 v[80:95], v[136:139], v[116:119], v[80:95]
	global_load_lds_dwordx4 v251, s[22:23]
	s_nop 1
	s_add_i32 m0, s59, 0xfffff000
	v_mfma_f32_32x32x16_bf16 v[80:95], v[144:147], v[120:123], v[80:95]
	global_load_lds_dwordx4 v252, s[22:23]
	v_exp_f32_e32 v96, v96
	v_exp_f32_e32 v97, v97
	v_exp_f32_e32 v98, v98
	s_add_i32 m0, s61, 0xfffff000
	v_mfma_f32_32x32x16_bf16 v[80:95], v[152:155], v[124:127], v[80:95]
	global_load_lds_dwordx4 v195, s[22:23]
	v_exp_f32_e32 v99, v99
	v_exp_f32_e32 v100, v100
	v_exp_f32_e32 v101, v101
	v_exp_f32_e32 v102, v102
	v_exp_f32_e32 v103, v103
	v_cvt_pk_bf16_f32 v208, v96, v97
	v_cvt_pk_bf16_f32 v209, v98, v99
	v_cvt_pk_bf16_f32 v210, v100, v101
	v_cvt_pk_bf16_f32 v211, v102, v103
	v_exp_f32_e32 v104, v104
	v_exp_f32_e32 v105, v105
	s_waitcnt lgkmcnt(6)
	v_mfma_f32_32x32x16_bf16 v[48:63], v[224:227], v[208:211], v[48:63]
	v_exp_f32_e32 v106, v106
	v_exp_f32_e32 v107, v107
	v_exp_f32_e32 v108, v108
	ds_read_b64_tr_b16 v[136:137], v178 offset:53248
	ds_read_b64_tr_b16 v[138:139], v179 offset:55296
	v_mfma_f32_32x32x16_bf16 v[32:47], v[228:231], v[208:211], v[32:47]
	v_exp_f32_e32 v109, v109
	v_exp_f32_e32 v110, v110
	v_exp_f32_e32 v111, v111
	ds_read_b64_tr_b16 v[144:145], v174 offset:57344
	ds_read_b64_tr_b16 v[146:147], v175 offset:59392
	v_mfma_f32_32x32x16_bf16 v[16:31], v[232:235], v[208:211], v[16:31]
	v_cvt_pk_bf16_f32 v212, v104, v105
	v_cvt_pk_bf16_f32 v213, v106, v107
	v_cvt_pk_bf16_f32 v214, v108, v109
	v_cvt_pk_bf16_f32 v215, v110, v111
	v_add_f32_e32 v187, v96, v187
	v_add_f32_e32 v192, v97, v192
	ds_read_b64_tr_b16 v[148:149], v176 offset:57344
	ds_read_b64_tr_b16 v[150:151], v177 offset:59392
	v_mfma_f32_32x32x16_bf16 v[0:15], v[236:239], v[208:211], v[0:15]
	v_add_f32_e32 v193, v98, v193
	v_add_f32_e32 v194, v99, v194
	v_add_f32_e32 v187, v100, v187
	v_add_f32_e32 v192, v101, v192
	v_add_f32_e32 v193, v102, v193
	v_add_f32_e32 v194, v103, v194
	ds_read_b64_tr_b16 v[152:153], v178 offset:57344
	ds_read_b64_tr_b16 v[154:155], v179 offset:59392
	s_waitcnt lgkmcnt(6)
	v_mfma_f32_32x32x16_bf16 v[48:63], v[128:131], v[212:215], v[48:63]
	v_exp_f32_e32 v80, v80
	v_exp_f32_e32 v81, v81
	v_exp_f32_e32 v82, v82
	ds_read_b64_tr_b16 v[240:241], v183 offset:57344
	ds_read_b64_tr_b16 v[242:243], v184 offset:59392
	ds_read_b128 v[128:131], v188 offset:8192
	v_mfma_f32_32x32x16_bf16 v[32:47], v[132:135], v[212:215], v[32:47]
	v_exp_f32_e32 v83, v83
	v_exp_f32_e32 v84, v84
	v_exp_f32_e32 v85, v85
	ds_read_b64_tr_b16 v[196:197], v174 offset:61440
	ds_read_b64_tr_b16 v[198:199], v175 offset:63488
	ds_read_b128 v[132:135], v189
	v_mfma_f32_32x32x16_bf16 v[16:31], v[136:139], v[212:215], v[16:31]
	v_exp_f32_e32 v86, v86
	v_exp_f32_e32 v87, v87
	v_cvt_pk_bf16_f32 v216, v80, v81
	v_cvt_pk_bf16_f32 v217, v82, v83
	ds_read_b64_tr_b16 v[200:201], v176 offset:61440
	ds_read_b64_tr_b16 v[202:203], v177 offset:63488
	ds_read_b128 v[136:139], v189 offset:8192
	v_mfma_f32_32x32x16_bf16 v[0:15], v[140:143], v[212:215], v[0:15]
	v_cvt_pk_bf16_f32 v218, v84, v85
	v_cvt_pk_bf16_f32 v219, v86, v87
	v_add_f32_e32 v187, v104, v187
	v_add_f32_e32 v192, v105, v192
	v_add_f32_e32 v193, v106, v193
	v_add_f32_e32 v194, v107, v194
	s_waitcnt lgkmcnt(12)
	ds_read_b64_tr_b16 v[204:205], v178 offset:61440
	ds_read_b64_tr_b16 v[206:207], v179 offset:63488
	ds_read_b128 v[140:143], v190
	s_waitcnt lgkmcnt(10)
	v_mfma_f32_32x32x16_bf16 v[48:63], v[144:147], v[216:219], v[48:63]
	v_exp_f32_e32 v88, v88
	v_exp_f32_e32 v89, v89
	v_exp_f32_e32 v90, v90
	ds_read_b64_tr_b16 v[246:247], v183 offset:61440
	ds_read_b64_tr_b16 v[248:249], v184 offset:63488
	ds_read_b128 v[144:147], v190 offset:8192
	v_mfma_f32_32x32x16_bf16 v[32:47], v[148:151], v[216:219], v[32:47]
	v_exp_f32_e32 v91, v91
	v_exp_f32_e32 v92, v92
	v_exp_f32_e32 v93, v93
	ds_read_b128 v[148:151], v191
	v_mfma_f32_32x32x16_bf16 v[16:31], v[152:155], v[216:219], v[16:31]
	v_exp_f32_e32 v94, v94
	v_exp_f32_e32 v95, v95
	v_cvt_pk_bf16_f32 v220, v88, v89
	v_cvt_pk_bf16_f32 v221, v90, v91
	ds_read_b128 v[152:155], v191 offset:8192
	v_mfma_f32_32x32x16_bf16 v[0:15], v[240:243], v[216:219], v[0:15]
	v_cvt_pk_bf16_f32 v222, v92, v93
	v_cvt_pk_bf16_f32 v223, v94, v95
	v_add_f32_e32 v187, v80, v187
	v_add_f32_e32 v192, v81, v192
	v_add_f32_e32 v193, v82, v193
	v_add_f32_e32 v194, v83, v194
	s_waitcnt lgkmcnt(3)
	v_mfma_f32_32x32x16_bf16 v[48:63], v[196:199], v[220:223], v[48:63]
	v_add_f32_e32 v187, v108, v187
	v_add_f32_e32 v192, v109, v192
	v_add_f32_e32 v193, v110, v193
	v_add_f32_e32 v194, v111, v194
	v_add_f32_e32 v187, v84, v187
	v_add_f32_e32 v192, v85, v192
	ds_read_b128 v[80:83], v188
	ds_read_b64_tr_b16 v[224:225], v174
	ds_read_b64_tr_b16 v[226:227], v175 offset:2048
	v_mfma_f32_32x32x16_bf16 v[32:47], v[200:203], v[220:223], v[32:47]
	v_add_f32_e32 v193, v86, v193
	v_add_f32_e32 v194, v87, v194
	v_add_f32_e32 v187, v88, v187
	v_add_f32_e32 v192, v89, v192
	v_add_f32_e32 v193, v90, v193
	v_add_f32_e32 v194, v91, v194
	ds_read_b64_tr_b16 v[228:229], v176
	ds_read_b64_tr_b16 v[230:231], v177 offset:2048
	v_mfma_f32_32x32x16_bf16 v[16:31], v[204:207], v[220:223], v[16:31]
	v_add_f32_e32 v187, v92, v187
	v_add_f32_e32 v192, v93, v192
	v_add_f32_e32 v193, v94, v193
	v_add_f32_e32 v194, v95, v194
	ds_read_b64_tr_b16 v[232:233], v178
	ds_read_b64_tr_b16 v[234:235], v179 offset:2048
	v_mfma_f32_32x32x16_bf16 v[0:15], v[246:249], v[220:223], v[0:15]
	ds_read_b64_tr_b16 v[236:237], v183
	ds_read_b64_tr_b16 v[238:239], v184 offset:2048
	s_min_u32 s10, s68, s24
	s_lshl_b32 s10, s10, 15
	s_add_u32 s4, s20, s10
	s_addc_u32 s5, s21, 0
	s_waitcnt vmcnt(8)
	s_add_i32 s68, s68, 4
	s_cmp_ge_u32 s69, s42
	s_barrier
	s_cbranch_scc0 .LG_loop
; #define LAS __attribute__((address_space(3)))
; #define DMA_WAIT_BAR() do { asm volatile("s_waitcnt vmcnt(0)" ::: "memory"); __syncthreads(); } while (0)
; __device__ __forceinline__ void attn_unit(LAS unsigned char* L, bf16_t* QKV, size_t rowbase, int S, int h, int qb, float lam, const float* subln, unsigned* kmax) {
;     ...
;     DMA_WAIT_BAR();
;     ...
;     lsum = (lsum + lsb) + (lsc + lsd);
;     const float inv = 1.f / (lsum + __shfl_xor(lsum, 32));
;     LAS float* X = (LAS float*)L;
;     const int xo = (32 * qblk + r32) * AXP + 4 * hi;
;     if (hd == 1) { const float sc = inv * lam;
; #pragma unroll
;         for (int d = 0; d < 4; ++d)
; #pragma unroll
;             for (int rg = 0; rg < 4; ++rg) *(LAS f32x4*)(X + xo + 32 * d + 8 * rg) = (f32x4){o[d][4 * rg] * sc, o[d][4 * rg + 1] * sc, o[d][4 * rg + 2] * sc, o[d][4 * rg + 3] * sc}; }
.Lattn_join:
	s_setprio 0
	v_add_f32_e32 v64, v187, v192
	v_add_f32_e32 v65, v193, v194
	v_add_f32_e32 v64, v64, v65
	ds_bpermute_b32 v65, v156, v64
	s_waitcnt vmcnt(0)
	s_cmp_eq_u32 s40, 1
	s_waitcnt lgkmcnt(0)
	s_barrier
	v_add_f32_e32 v64, v64, v65
	v_div_scale_f32 v65, s[4:5], v64, v64, 1.0
	v_rcp_f32_e32 v66, v65
	s_nop 0
	v_fma_f32 v67, -v65, v66, 1.0
	v_fmac_f32_e32 v66, v67, v66
	v_div_scale_f32 v67, vcc, 1.0, v64, 1.0
	v_mul_f32_e32 v68, v67, v66
	v_fma_f32 v69, -v65, v68, v67
	v_fmac_f32_e32 v68, v69, v66
	v_fma_f32 v65, -v65, v68, v67
	v_div_fmas_f32 v65, v65, v66, v68
	v_div_fixup_f32 v66, v65, v64, 1.0
	v_or_b32_e32 v64, s41, v182
	v_mad_u32_u24 v64, v64, s38, v158
	v_lshl_add_u32 v64, v64, 2, 0
	s_cbranch_scc0 .LBB0_930
	v_mul_f32_e32 v72, v159, v66
	v_pk_mul_f32 v[68:69], v[48:49], v[72:73] op_sel_hi:[1,0]
	v_pk_mul_f32 v[70:71], v[50:51], v[72:73] op_sel_hi:[1,0]
	ds_write_b128 v64, v[68:71]
	v_pk_mul_f32 v[68:69], v[52:53], v[72:73] op_sel_hi:[1,0]
	v_pk_mul_f32 v[70:71], v[54:55], v[72:73] op_sel_hi:[1,0]
	ds_write_b128 v64, v[68:71] offset:32
	v_pk_mul_f32 v[68:69], v[56:57], v[72:73] op_sel_hi:[1,0]
	v_pk_mul_f32 v[70:71], v[58:59], v[72:73] op_sel_hi:[1,0]
	ds_write_b128 v64, v[68:71] offset:64
	v_pk_mul_f32 v[68:69], v[60:61], v[72:73] op_sel_hi:[1,0]
	v_pk_mul_f32 v[70:71], v[62:63], v[72:73] op_sel_hi:[1,0]
	ds_write_b128 v64, v[68:71] offset:96
	v_pk_mul_f32 v[68:69], v[32:33], v[72:73] op_sel_hi:[1,0]
	v_pk_mul_f32 v[70:71], v[34:35], v[72:73] op_sel_hi:[1,0]
	ds_write_b128 v64, v[68:71] offset:128
	v_pk_mul_f32 v[68:69], v[36:37], v[72:73] op_sel_hi:[1,0]
	v_pk_mul_f32 v[70:71], v[38:39], v[72:73] op_sel_hi:[1,0]
	ds_write_b128 v64, v[68:71] offset:160
	v_pk_mul_f32 v[68:69], v[40:41], v[72:73] op_sel_hi:[1,0]
	v_pk_mul_f32 v[70:71], v[42:43], v[72:73] op_sel_hi:[1,0]
	ds_write_b128 v64, v[68:71] offset:192
	v_pk_mul_f32 v[68:69], v[44:45], v[72:73] op_sel_hi:[1,0]
	v_pk_mul_f32 v[70:71], v[46:47], v[72:73] op_sel_hi:[1,0]
	ds_write_b128 v64, v[68:71] offset:224
	v_pk_mul_f32 v[68:69], v[16:17], v[72:73] op_sel_hi:[1,0]
	v_pk_mul_f32 v[70:71], v[18:19], v[72:73] op_sel_hi:[1,0]
	ds_write_b128 v64, v[68:71] offset:256
	v_pk_mul_f32 v[68:69], v[20:21], v[72:73] op_sel_hi:[1,0]
	v_pk_mul_f32 v[70:71], v[22:23], v[72:73] op_sel_hi:[1,0]
	ds_write_b128 v64, v[68:71] offset:288
	v_pk_mul_f32 v[68:69], v[24:25], v[72:73] op_sel_hi:[1,0]
	v_pk_mul_f32 v[70:71], v[26:27], v[72:73] op_sel_hi:[1,0]
	ds_write_b128 v64, v[68:71] offset:320
	v_pk_mul_f32 v[68:69], v[28:29], v[72:73] op_sel_hi:[1,0]
	v_pk_mul_f32 v[70:71], v[30:31], v[72:73] op_sel_hi:[1,0]
	ds_write_b128 v64, v[68:71] offset:352
	v_pk_mul_f32 v[68:69], v[0:1], v[72:73] op_sel_hi:[1,0]
	v_pk_mul_f32 v[70:71], v[2:3], v[72:73] op_sel_hi:[1,0]
	ds_write_b128 v64, v[68:71] offset:384
	v_pk_mul_f32 v[68:69], v[4:5], v[72:73] op_sel_hi:[1,0]
	v_pk_mul_f32 v[70:71], v[6:7], v[72:73] op_sel_hi:[1,0]
	ds_write_b128 v64, v[68:71] offset:416
	v_pk_mul_f32 v[68:69], v[8:9], v[72:73] op_sel_hi:[1,0]
	v_pk_mul_f32 v[70:71], v[10:11], v[72:73] op_sel_hi:[1,0]
	ds_write_b128 v64, v[68:71] offset:448
	v_pk_mul_f32 v[68:69], v[12:13], v[72:73] op_sel_hi:[1,0]
	v_pk_mul_f32 v[70:71], v[14:15], v[72:73] op_sel_hi:[1,0]
	ds_write_b128 v64, v[68:71] offset:480
